# tail transposes balanced: busy workgroups of the last tile round also convert 1 item per wave after their tile; idle ones 11 per wave
# baseline (speedup 1.0000x reference)
.LBB0_363:
	s_waitcnt vmcnt(0)
	s_barrier
	s_cmp_lg_u32 s87, 0x100
	s_cbranch_scc1 .Ltt2_0_done
	s_cmp_lt_u32 s96, 128
	s_cbranch_scc1 .Ltt2_0_done
	s_cmp_ge_u32 s96, 256
	s_cbranch_scc1 .Ltt2_0_done
	s_sub_u32 s20, s96, 128
	s_lshl_b32 s20, s20, 3
	s_add_u32 s20, s20, s93
	s_movk_i32 s23, 1024
	v_mbcnt_hi_u32_b32 v0, -1, v212
	v_and_b32_e32 v0, 63, v0
	v_lshrrev_b32_e32 v1, 3, v0
	v_and_b32_e32 v2, 7, v0
	s_lshl_b32 s25, s93, 14
	v_mul_u32_u24_e32 v3, 0x84, v1
	v_mul_u32_u24_e32 v4, 0x420, v2
	v_lshlrev_b32_e32 v2, 4, v2
	v_add3_u32 v3, v3, v2, s25
	v_lshl_add_u32 v4, v1, 2, v4
	v_add_u32_e32 v4, s25, v4
	v_and_b32_e32 v7, 4, v1
	v_and_b32_e32 v5, 3, v1
	v_lshl_add_u32 v7, v7, 1, v5
	v_readlane_b32 s62, v245, 0
	v_readlane_b32 s63, v245, 1
	s_add_u32 s64, s76, 0x4989000
	s_addc_u32 s65, s77, 0
	v_readlane_b32 s66, v244, 21
	v_readlane_b32 s67, v244, 22
	s_add_u32 s68, s76, 0x8989000
	s_addc_u32 s69, s77, 0
	s_cmp_ge_u32 s20, 11264
	s_cbranch_scc1 .Ltt2_0_done
	s_cmp_lt_u32 s20, 8192
	s_cbranch_scc1 .Ltt2_0_r1_s0
	s_sub_u32 s25, s20, 8192
	s_lshr_b32 s27, s25, 6
	s_and_b32 s31, s25, 63
	s_mul_i32 s35, s27, 0x80000
	s_lshl_b32 s41, s31, 7
	s_add_u32 s35, s35, s41
	s_add_u32 s0, s66, s35
	s_addc_u32 s1, s67, 0
	s_mul_i32 s35, s31, 0x80000
	s_lshl_b32 s41, s27, 7
	s_add_u32 s35, s35, s41
	s_add_u32 s2, s68, s35
	s_addc_u32 s3, s69, 0
	s_mov_b32 s5, 0x2000
	s_mov_b32 s6, 0x10000
	s_mov_b32 s7, 0x4000
	s_branch .Ltt2_0_r1_e

.Ltt2_0_r1_e:
	v_mad_u32_u24 v5, v1, s5, v2
	global_load_dwordx4 v[8:11], v5, s[0:1] nt
	s_add_u32 s0, s0, s6
	s_addc_u32 s1, s1, 0
	global_load_dwordx4 v[12:15], v5, s[0:1] nt
	s_add_u32 s0, s0, s6
	s_addc_u32 s1, s1, 0
	global_load_dwordx4 v[16:19], v5, s[0:1] nt
	s_add_u32 s0, s0, s6
	s_addc_u32 s1, s1, 0
	global_load_dwordx4 v[20:23], v5, s[0:1] nt
	s_add_u32 s0, s0, s6
	s_addc_u32 s1, s1, 0
	global_load_dwordx4 v[24:27], v5, s[0:1] nt
	s_add_u32 s0, s0, s6
	s_addc_u32 s1, s1, 0
	global_load_dwordx4 v[28:31], v5, s[0:1] nt
	s_add_u32 s0, s0, s6
	s_addc_u32 s1, s1, 0
	global_load_dwordx4 v[32:35], v5, s[0:1] nt
	s_add_u32 s0, s0, s6
	s_addc_u32 s1, s1, 0
	global_load_dwordx4 v[36:39], v5, s[0:1] nt
	s_add_u32 s0, s0, s6
	s_addc_u32 s1, s1, 0
	s_add_u32 s20, s20, s23
	s_cmp_ge_u32 s20, 11264
	s_cbranch_scc1 .Ltt2_0_dr1
	s_cmp_lt_u32 s20, 8192
	s_cbranch_scc1 .Ltt2_0_r2_s0
	s_sub_u32 s25, s20, 8192
	s_lshr_b32 s27, s25, 6
	s_and_b32 s31, s25, 63
	s_mul_i32 s35, s27, 0x80000
	s_lshl_b32 s41, s31, 7
	s_add_u32 s35, s35, s41
	s_add_u32 s0, s66, s35
	s_addc_u32 s1, s67, 0
	s_mul_i32 s35, s31, 0x80000
	s_lshl_b32 s41, s27, 7
	s_add_u32 s35, s35, s41
	s_add_u32 s10, s68, s35
	s_addc_u32 s11, s69, 0
	s_mov_b32 s5, 0x2000
	s_mov_b32 s6, 0x10000
	s_mov_b32 s47, 0x4000
	s_branch .Ltt2_0_r2_e

.Ltt2_0_r2_e:
	v_mad_u32_u24 v5, v1, s5, v2
	global_load_dwordx4 v[40:43], v5, s[0:1] nt
	s_add_u32 s0, s0, s6
	s_addc_u32 s1, s1, 0
	global_load_dwordx4 v[44:47], v5, s[0:1] nt
	s_add_u32 s0, s0, s6
	s_addc_u32 s1, s1, 0
	global_load_dwordx4 v[48:51], v5, s[0:1] nt
	s_add_u32 s0, s0, s6
	s_addc_u32 s1, s1, 0
	global_load_dwordx4 v[52:55], v5, s[0:1] nt
	s_add_u32 s0, s0, s6
	s_addc_u32 s1, s1, 0
	global_load_dwordx4 v[56:59], v5, s[0:1] nt
	s_add_u32 s0, s0, s6
	s_addc_u32 s1, s1, 0
	global_load_dwordx4 v[60:63], v5, s[0:1] nt
	s_add_u32 s0, s0, s6
	s_addc_u32 s1, s1, 0
	global_load_dwordx4 v[64:67], v5, s[0:1] nt
	s_add_u32 s0, s0, s6
	s_addc_u32 s1, s1, 0
	global_load_dwordx4 v[68:71], v5, s[0:1] nt
	s_add_u32 s0, s0, s6
	s_addc_u32 s1, s1, 0
	s_add_u32 s20, s20, s23
	s_cmp_ge_u32 s20, 11264
	s_cbranch_scc1 .Ltt2_0_dr2
	s_cmp_lt_u32 s20, 8192
	s_cbranch_scc1 .Ltt2_0_r3_s0
	s_sub_u32 s25, s20, 8192
	s_lshr_b32 s27, s25, 6
	s_and_b32 s31, s25, 63
	s_mul_i32 s35, s27, 0x80000
	s_lshl_b32 s41, s31, 7
	s_add_u32 s35, s35, s41
	s_add_u32 s0, s66, s35
	s_addc_u32 s1, s67, 0
	s_mul_i32 s35, s31, 0x80000
	s_lshl_b32 s41, s27, 7
	s_add_u32 s35, s35, s41
	s_add_u32 s42, s68, s35
	s_addc_u32 s43, s69, 0
	s_mov_b32 s5, 0x2000
	s_mov_b32 s6, 0x10000
	s_mov_b32 s44, 0x4000
	s_branch .Ltt2_0_r3_e

.Ltt2_0_r3_e:
	v_mad_u32_u24 v5, v1, s5, v2
	global_load_dwordx4 v[72:75], v5, s[0:1] nt
	s_add_u32 s0, s0, s6
	s_addc_u32 s1, s1, 0
	global_load_dwordx4 v[76:79], v5, s[0:1] nt
	s_add_u32 s0, s0, s6
	s_addc_u32 s1, s1, 0
	global_load_dwordx4 v[80:83], v5, s[0:1] nt
	s_add_u32 s0, s0, s6
	s_addc_u32 s1, s1, 0
	global_load_dwordx4 v[84:87], v5, s[0:1] nt
	s_add_u32 s0, s0, s6
	s_addc_u32 s1, s1, 0
	global_load_dwordx4 v[88:91], v5, s[0:1] nt
	s_add_u32 s0, s0, s6
	s_addc_u32 s1, s1, 0
	global_load_dwordx4 v[92:95], v5, s[0:1] nt
	s_add_u32 s0, s0, s6
	s_addc_u32 s1, s1, 0
	global_load_dwordx4 v[96:99], v5, s[0:1] nt
	s_add_u32 s0, s0, s6
	s_addc_u32 s1, s1, 0
	global_load_dwordx4 v[100:103], v5, s[0:1] nt
	s_add_u32 s0, s0, s6
	s_addc_u32 s1, s1, 0
	s_add_u32 s20, s20, s23
	s_waitcnt vmcnt(16)
	ds_write_b32 v3, v8 offset:0
	ds_write_b32 v3, v9 offset:4
	ds_write_b32 v3, v10 offset:8
	ds_write_b32 v3, v11 offset:12
	ds_write_b32 v3, v12 offset:1056
	ds_write_b32 v3, v13 offset:1060
	ds_write_b32 v3, v14 offset:1064
	ds_write_b32 v3, v15 offset:1068
	ds_write_b32 v3, v16 offset:2112
	ds_write_b32 v3, v17 offset:2116
	ds_write_b32 v3, v18 offset:2120
	ds_write_b32 v3, v19 offset:2124
	ds_write_b32 v3, v20 offset:3168
	ds_write_b32 v3, v21 offset:3172
	ds_write_b32 v3, v22 offset:3176
	ds_write_b32 v3, v23 offset:3180
	ds_write_b32 v3, v24 offset:4224
	ds_write_b32 v3, v25 offset:4228
	ds_write_b32 v3, v26 offset:4232
	ds_write_b32 v3, v27 offset:4236
	ds_write_b32 v3, v28 offset:5280
	ds_write_b32 v3, v29 offset:5284
	ds_write_b32 v3, v30 offset:5288
	ds_write_b32 v3, v31 offset:5292
	ds_write_b32 v3, v32 offset:6336
	ds_write_b32 v3, v33 offset:6340
	ds_write_b32 v3, v34 offset:6344
	ds_write_b32 v3, v35 offset:6348
	ds_write_b32 v3, v36 offset:7392
	ds_write_b32 v3, v37 offset:7396
	ds_write_b32 v3, v38 offset:7400
	ds_write_b32 v3, v39 offset:7404
	s_mov_b32 s32, s2
	s_mov_b32 s33, s3
	s_lshl_b32 s49, s7, 3
	v_mad_u32_u24 v6, v1, s7, v2
	s_waitcnt lgkmcnt(0)
	ds_read_b32 v104, v4 offset:0
	ds_read_b32 v105, v4 offset:132
	ds_read_b32 v106, v4 offset:264
	ds_read_b32 v107, v4 offset:396
	ds_read_b32 v108, v4 offset:528
	ds_read_b32 v109, v4 offset:660
	ds_read_b32 v110, v4 offset:792
	ds_read_b32 v111, v4 offset:924
	ds_read_b32 v112, v4 offset:32
	ds_read_b32 v113, v4 offset:164
	ds_read_b32 v114, v4 offset:296
	ds_read_b32 v115, v4 offset:428
	ds_read_b32 v116, v4 offset:560
	ds_read_b32 v117, v4 offset:692
	ds_read_b32 v118, v4 offset:824
	ds_read_b32 v119, v4 offset:956
	s_waitcnt lgkmcnt(8)
	v_cvt_pk_bf16_f32 v136, v104, v105
	v_cvt_pk_bf16_f32 v137, v106, v107
	v_cvt_pk_bf16_f32 v138, v108, v109
	v_cvt_pk_bf16_f32 v139, v110, v111
	global_store_dwordx4 v6, v[136:139], s[32:33] nt
	s_add_u32 s32, s32, s49
	s_addc_u32 s33, s33, 0
	ds_read_b32 v120, v4 offset:64
	ds_read_b32 v121, v4 offset:196
	ds_read_b32 v122, v4 offset:328
	ds_read_b32 v123, v4 offset:460
	ds_read_b32 v124, v4 offset:592
	ds_read_b32 v125, v4 offset:724
	ds_read_b32 v126, v4 offset:856
	ds_read_b32 v127, v4 offset:988
	s_waitcnt lgkmcnt(8)
	v_cvt_pk_bf16_f32 v140, v112, v113
	v_cvt_pk_bf16_f32 v141, v114, v115
	v_cvt_pk_bf16_f32 v142, v116, v117
	v_cvt_pk_bf16_f32 v143, v118, v119
	global_store_dwordx4 v6, v[140:143], s[32:33] nt
	s_add_u32 s32, s32, s49
	s_addc_u32 s33, s33, 0
	ds_read_b32 v128, v4 offset:96
	ds_read_b32 v129, v4 offset:228
	ds_read_b32 v130, v4 offset:360
	ds_read_b32 v131, v4 offset:492
	ds_read_b32 v132, v4 offset:624
	ds_read_b32 v133, v4 offset:756
	ds_read_b32 v134, v4 offset:888
	ds_read_b32 v135, v4 offset:1020
	s_waitcnt lgkmcnt(8)
	v_cvt_pk_bf16_f32 v136, v120, v121
	v_cvt_pk_bf16_f32 v137, v122, v123
	v_cvt_pk_bf16_f32 v138, v124, v125
	v_cvt_pk_bf16_f32 v139, v126, v127
	global_store_dwordx4 v6, v[136:139], s[32:33] nt
	s_add_u32 s32, s32, s49
	s_addc_u32 s33, s33, 0
	s_waitcnt lgkmcnt(0)
	v_cvt_pk_bf16_f32 v140, v128, v129
	v_cvt_pk_bf16_f32 v141, v130, v131
	v_cvt_pk_bf16_f32 v142, v132, v133
	v_cvt_pk_bf16_f32 v143, v134, v135
	global_store_dwordx4 v6, v[140:143], s[32:33] nt
	s_add_u32 s32, s32, s49
	s_addc_u32 s33, s33, 0
	s_cmp_ge_u32 s20, 11264
	s_cbranch_scc1 .Ltt2_0_dr3
	s_cmp_lt_u32 s20, 8192
	s_cbranch_scc1 .Ltt2_0_r4_s0
	s_sub_u32 s25, s20, 8192
	s_lshr_b32 s27, s25, 6
	s_and_b32 s31, s25, 63
	s_mul_i32 s35, s27, 0x80000
	s_lshl_b32 s41, s31, 7
	s_add_u32 s35, s35, s41
	s_add_u32 s0, s66, s35
	s_addc_u32 s1, s67, 0
	s_mul_i32 s35, s31, 0x80000
	s_lshl_b32 s41, s27, 7
	s_add_u32 s35, s35, s41
	s_add_u32 s2, s68, s35
	s_addc_u32 s3, s69, 0
	s_mov_b32 s5, 0x2000
	s_mov_b32 s6, 0x10000
	s_mov_b32 s7, 0x4000
	s_branch .Ltt2_0_r4_e

.Ltt2_0_loop:
	s_cmp_ge_u32 s20, 11264
	s_cbranch_scc1 .Ltt2_0_dr4
	s_cmp_lt_u32 s20, 8192
	s_cbranch_scc1 .Ltt2_0_r5_s0
	s_sub_u32 s25, s20, 8192
	s_lshr_b32 s27, s25, 6
	s_and_b32 s31, s25, 63
	s_mul_i32 s35, s27, 0x80000
	s_lshl_b32 s41, s31, 7
	s_add_u32 s35, s35, s41
	s_add_u32 s0, s66, s35
	s_addc_u32 s1, s67, 0
	s_mul_i32 s35, s31, 0x80000
	s_lshl_b32 s41, s27, 7
	s_add_u32 s35, s35, s41
	s_add_u32 s10, s68, s35
	s_addc_u32 s11, s69, 0
	s_mov_b32 s5, 0x2000
	s_mov_b32 s6, 0x10000
	s_mov_b32 s47, 0x4000
	s_branch .Ltt2_0_r5_e

.Ltt2_0_r5_e:
	v_mad_u32_u24 v5, v1, s5, v2
	global_load_dwordx4 v[40:43], v5, s[0:1] nt
	s_add_u32 s0, s0, s6
	s_addc_u32 s1, s1, 0
	global_load_dwordx4 v[44:47], v5, s[0:1] nt
	s_add_u32 s0, s0, s6
	s_addc_u32 s1, s1, 0
	global_load_dwordx4 v[48:51], v5, s[0:1] nt
	s_add_u32 s0, s0, s6
	s_addc_u32 s1, s1, 0
	global_load_dwordx4 v[52:55], v5, s[0:1] nt
	s_add_u32 s0, s0, s6
	s_addc_u32 s1, s1, 0
	global_load_dwordx4 v[56:59], v5, s[0:1] nt
	s_add_u32 s0, s0, s6
	s_addc_u32 s1, s1, 0
	global_load_dwordx4 v[60:63], v5, s[0:1] nt
	s_add_u32 s0, s0, s6
	s_addc_u32 s1, s1, 0
	global_load_dwordx4 v[64:67], v5, s[0:1] nt
	s_add_u32 s0, s0, s6
	s_addc_u32 s1, s1, 0
	global_load_dwordx4 v[68:71], v5, s[0:1] nt
	s_add_u32 s0, s0, s6
	s_addc_u32 s1, s1, 0
	s_add_u32 s20, s20, s23
	s_waitcnt vmcnt(24)
	ds_write_b32 v3, v72 offset:0
	ds_write_b32 v3, v73 offset:4
	ds_write_b32 v3, v74 offset:8
	ds_write_b32 v3, v75 offset:12
	ds_write_b32 v3, v76 offset:1056
	ds_write_b32 v3, v77 offset:1060
	ds_write_b32 v3, v78 offset:1064
	ds_write_b32 v3, v79 offset:1068
	ds_write_b32 v3, v80 offset:2112
	ds_write_b32 v3, v81 offset:2116
	ds_write_b32 v3, v82 offset:2120
	ds_write_b32 v3, v83 offset:2124
	ds_write_b32 v3, v84 offset:3168
	ds_write_b32 v3, v85 offset:3172
	ds_write_b32 v3, v86 offset:3176
	ds_write_b32 v3, v87 offset:3180
	ds_write_b32 v3, v88 offset:4224
	ds_write_b32 v3, v89 offset:4228
	ds_write_b32 v3, v90 offset:4232
	ds_write_b32 v3, v91 offset:4236
	ds_write_b32 v3, v92 offset:5280
	ds_write_b32 v3, v93 offset:5284
	ds_write_b32 v3, v94 offset:5288
	ds_write_b32 v3, v95 offset:5292
	ds_write_b32 v3, v96 offset:6336
	ds_write_b32 v3, v97 offset:6340
	ds_write_b32 v3, v98 offset:6344
	ds_write_b32 v3, v99 offset:6348
	ds_write_b32 v3, v100 offset:7392
	ds_write_b32 v3, v101 offset:7396
	ds_write_b32 v3, v102 offset:7400
	ds_write_b32 v3, v103 offset:7404
	s_mov_b32 s32, s42
	s_mov_b32 s33, s43
	s_lshl_b32 s49, s44, 3
	v_mad_u32_u24 v6, v1, s44, v2
	s_waitcnt lgkmcnt(0)
	ds_read_b32 v104, v4 offset:0
	ds_read_b32 v105, v4 offset:132
	ds_read_b32 v106, v4 offset:264
	ds_read_b32 v107, v4 offset:396
	ds_read_b32 v108, v4 offset:528
	ds_read_b32 v109, v4 offset:660
	ds_read_b32 v110, v4 offset:792
	ds_read_b32 v111, v4 offset:924
	ds_read_b32 v112, v4 offset:32
	ds_read_b32 v113, v4 offset:164
	ds_read_b32 v114, v4 offset:296
	ds_read_b32 v115, v4 offset:428
	ds_read_b32 v116, v4 offset:560
	ds_read_b32 v117, v4 offset:692
	ds_read_b32 v118, v4 offset:824
	ds_read_b32 v119, v4 offset:956
	s_waitcnt lgkmcnt(8)
	v_cvt_pk_bf16_f32 v136, v104, v105
	v_cvt_pk_bf16_f32 v137, v106, v107
	v_cvt_pk_bf16_f32 v138, v108, v109
	v_cvt_pk_bf16_f32 v139, v110, v111
	global_store_dwordx4 v6, v[136:139], s[32:33] nt
	s_add_u32 s32, s32, s49
	s_addc_u32 s33, s33, 0
	ds_read_b32 v120, v4 offset:64
	ds_read_b32 v121, v4 offset:196
	ds_read_b32 v122, v4 offset:328
	ds_read_b32 v123, v4 offset:460
	ds_read_b32 v124, v4 offset:592
	ds_read_b32 v125, v4 offset:724
	ds_read_b32 v126, v4 offset:856
	ds_read_b32 v127, v4 offset:988
	s_waitcnt lgkmcnt(8)
	v_cvt_pk_bf16_f32 v140, v112, v113
	v_cvt_pk_bf16_f32 v141, v114, v115
	v_cvt_pk_bf16_f32 v142, v116, v117
	v_cvt_pk_bf16_f32 v143, v118, v119
	global_store_dwordx4 v6, v[140:143], s[32:33] nt
	s_add_u32 s32, s32, s49
	s_addc_u32 s33, s33, 0
	ds_read_b32 v128, v4 offset:96
	ds_read_b32 v129, v4 offset:228
	ds_read_b32 v130, v4 offset:360
	ds_read_b32 v131, v4 offset:492
	ds_read_b32 v132, v4 offset:624
	ds_read_b32 v133, v4 offset:756
	ds_read_b32 v134, v4 offset:888
	ds_read_b32 v135, v4 offset:1020
	s_waitcnt lgkmcnt(8)
	v_cvt_pk_bf16_f32 v136, v120, v121
	v_cvt_pk_bf16_f32 v137, v122, v123
	v_cvt_pk_bf16_f32 v138, v124, v125
	v_cvt_pk_bf16_f32 v139, v126, v127
	global_store_dwordx4 v6, v[136:139], s[32:33] nt
	s_add_u32 s32, s32, s49
	s_addc_u32 s33, s33, 0
	s_waitcnt lgkmcnt(0)
	v_cvt_pk_bf16_f32 v140, v128, v129
	v_cvt_pk_bf16_f32 v141, v130, v131
	v_cvt_pk_bf16_f32 v142, v132, v133
	v_cvt_pk_bf16_f32 v143, v134, v135
	global_store_dwordx4 v6, v[140:143], s[32:33] nt
	s_add_u32 s32, s32, s49
	s_addc_u32 s33, s33, 0
	s_cmp_ge_u32 s20, 11264
	s_cbranch_scc1 .Ltt2_0_dr5
	s_cmp_lt_u32 s20, 8192
	s_cbranch_scc1 .Ltt2_0_r6_s0
	s_sub_u32 s25, s20, 8192
	s_lshr_b32 s27, s25, 6
	s_and_b32 s31, s25, 63
	s_mul_i32 s35, s27, 0x80000
	s_lshl_b32 s41, s31, 7
	s_add_u32 s35, s35, s41
	s_add_u32 s0, s66, s35
	s_addc_u32 s1, s67, 0
	s_mul_i32 s35, s31, 0x80000
	s_lshl_b32 s41, s27, 7
	s_add_u32 s35, s35, s41
	s_add_u32 s42, s68, s35
	s_addc_u32 s43, s69, 0
	s_mov_b32 s5, 0x2000
	s_mov_b32 s6, 0x10000
	s_mov_b32 s44, 0x4000
	s_branch .Ltt2_0_r6_e

.Ltt2_0_r6_e:
	v_mad_u32_u24 v5, v1, s5, v2
	global_load_dwordx4 v[72:75], v5, s[0:1] nt
	s_add_u32 s0, s0, s6
	s_addc_u32 s1, s1, 0
	global_load_dwordx4 v[76:79], v5, s[0:1] nt
	s_add_u32 s0, s0, s6
	s_addc_u32 s1, s1, 0
	global_load_dwordx4 v[80:83], v5, s[0:1] nt
	s_add_u32 s0, s0, s6
	s_addc_u32 s1, s1, 0
	global_load_dwordx4 v[84:87], v5, s[0:1] nt
	s_add_u32 s0, s0, s6
	s_addc_u32 s1, s1, 0
	global_load_dwordx4 v[88:91], v5, s[0:1] nt
	s_add_u32 s0, s0, s6
	s_addc_u32 s1, s1, 0
	global_load_dwordx4 v[92:95], v5, s[0:1] nt
	s_add_u32 s0, s0, s6
	s_addc_u32 s1, s1, 0
	global_load_dwordx4 v[96:99], v5, s[0:1] nt
	s_add_u32 s0, s0, s6
	s_addc_u32 s1, s1, 0
	global_load_dwordx4 v[100:103], v5, s[0:1] nt
	s_add_u32 s0, s0, s6
	s_addc_u32 s1, s1, 0
	s_add_u32 s20, s20, s23
	s_waitcnt vmcnt(24)
	ds_write_b32 v3, v8 offset:0
	ds_write_b32 v3, v9 offset:4
	ds_write_b32 v3, v10 offset:8
	ds_write_b32 v3, v11 offset:12
	ds_write_b32 v3, v12 offset:1056
	ds_write_b32 v3, v13 offset:1060
	ds_write_b32 v3, v14 offset:1064
	ds_write_b32 v3, v15 offset:1068
	ds_write_b32 v3, v16 offset:2112
	ds_write_b32 v3, v17 offset:2116
	ds_write_b32 v3, v18 offset:2120
	ds_write_b32 v3, v19 offset:2124
	ds_write_b32 v3, v20 offset:3168
	ds_write_b32 v3, v21 offset:3172
	ds_write_b32 v3, v22 offset:3176
	ds_write_b32 v3, v23 offset:3180
	ds_write_b32 v3, v24 offset:4224
	ds_write_b32 v3, v25 offset:4228
	ds_write_b32 v3, v26 offset:4232
	ds_write_b32 v3, v27 offset:4236
	ds_write_b32 v3, v28 offset:5280
	ds_write_b32 v3, v29 offset:5284
	ds_write_b32 v3, v30 offset:5288
	ds_write_b32 v3, v31 offset:5292
	ds_write_b32 v3, v32 offset:6336
	ds_write_b32 v3, v33 offset:6340
	ds_write_b32 v3, v34 offset:6344
	ds_write_b32 v3, v35 offset:6348
	ds_write_b32 v3, v36 offset:7392
	ds_write_b32 v3, v37 offset:7396
	ds_write_b32 v3, v38 offset:7400
	ds_write_b32 v3, v39 offset:7404
	s_mov_b32 s32, s2
	s_mov_b32 s33, s3
	s_lshl_b32 s49, s7, 3
	v_mad_u32_u24 v6, v1, s7, v2
	s_waitcnt lgkmcnt(0)
	ds_read_b32 v104, v4 offset:0
	ds_read_b32 v105, v4 offset:132
	ds_read_b32 v106, v4 offset:264
	ds_read_b32 v107, v4 offset:396
	ds_read_b32 v108, v4 offset:528
	ds_read_b32 v109, v4 offset:660
	ds_read_b32 v110, v4 offset:792
	ds_read_b32 v111, v4 offset:924
	ds_read_b32 v112, v4 offset:32
	ds_read_b32 v113, v4 offset:164
	ds_read_b32 v114, v4 offset:296
	ds_read_b32 v115, v4 offset:428
	ds_read_b32 v116, v4 offset:560
	ds_read_b32 v117, v4 offset:692
	ds_read_b32 v118, v4 offset:824
	ds_read_b32 v119, v4 offset:956
	s_waitcnt lgkmcnt(8)
	v_cvt_pk_bf16_f32 v136, v104, v105
	v_cvt_pk_bf16_f32 v137, v106, v107
	v_cvt_pk_bf16_f32 v138, v108, v109
	v_cvt_pk_bf16_f32 v139, v110, v111
	global_store_dwordx4 v6, v[136:139], s[32:33] nt
	s_add_u32 s32, s32, s49
	s_addc_u32 s33, s33, 0
	ds_read_b32 v120, v4 offset:64
	ds_read_b32 v121, v4 offset:196
	ds_read_b32 v122, v4 offset:328
	ds_read_b32 v123, v4 offset:460
	ds_read_b32 v124, v4 offset:592
	ds_read_b32 v125, v4 offset:724
	ds_read_b32 v126, v4 offset:856
	ds_read_b32 v127, v4 offset:988
	s_waitcnt lgkmcnt(8)
	v_cvt_pk_bf16_f32 v140, v112, v113
	v_cvt_pk_bf16_f32 v141, v114, v115
	v_cvt_pk_bf16_f32 v142, v116, v117
	v_cvt_pk_bf16_f32 v143, v118, v119
	global_store_dwordx4 v6, v[140:143], s[32:33] nt
	s_add_u32 s32, s32, s49
	s_addc_u32 s33, s33, 0
	ds_read_b32 v128, v4 offset:96
	ds_read_b32 v129, v4 offset:228
	ds_read_b32 v130, v4 offset:360
	ds_read_b32 v131, v4 offset:492
	ds_read_b32 v132, v4 offset:624
	ds_read_b32 v133, v4 offset:756
	ds_read_b32 v134, v4 offset:888
	ds_read_b32 v135, v4 offset:1020
	s_waitcnt lgkmcnt(8)
	v_cvt_pk_bf16_f32 v136, v120, v121
	v_cvt_pk_bf16_f32 v137, v122, v123
	v_cvt_pk_bf16_f32 v138, v124, v125
	v_cvt_pk_bf16_f32 v139, v126, v127
	global_store_dwordx4 v6, v[136:139], s[32:33] nt
	s_add_u32 s32, s32, s49
	s_addc_u32 s33, s33, 0
	s_waitcnt lgkmcnt(0)
	v_cvt_pk_bf16_f32 v140, v128, v129
	v_cvt_pk_bf16_f32 v141, v130, v131
	v_cvt_pk_bf16_f32 v142, v132, v133
	v_cvt_pk_bf16_f32 v143, v134, v135
	global_store_dwordx4 v6, v[140:143], s[32:33] nt
	s_add_u32 s32, s32, s49
	s_addc_u32 s33, s33, 0
	s_cmp_ge_u32 s20, 11264
	s_cbranch_scc1 .Ltt2_0_dr6
	s_cmp_lt_u32 s20, 8192
	s_cbranch_scc1 .Ltt2_0_r7_s0
	s_sub_u32 s25, s20, 8192
	s_lshr_b32 s27, s25, 6
	s_and_b32 s31, s25, 63
	s_mul_i32 s35, s27, 0x80000
	s_lshl_b32 s41, s31, 7
	s_add_u32 s35, s35, s41
	s_add_u32 s0, s66, s35
	s_addc_u32 s1, s67, 0
	s_mul_i32 s35, s31, 0x80000
	s_lshl_b32 s41, s27, 7
	s_add_u32 s35, s35, s41
	s_add_u32 s2, s68, s35
	s_addc_u32 s3, s69, 0
	s_mov_b32 s5, 0x2000
	s_mov_b32 s6, 0x10000
	s_mov_b32 s7, 0x4000
	s_branch .Ltt2_0_r7_e

.Ltt2_0_done:
	s_cmp_lg_u32 s87, 0x100
	s_cbranch_scc1 .Ltt2_1_done
	s_cmp_lt_u32 s96, 0
	s_cbranch_scc1 .Ltt2_1_done
	s_cmp_ge_u32 s96, 128
	s_cbranch_scc1 .Ltt2_1_done
	s_sub_u32 s20, s96, 0
	s_lshl_b32 s20, s20, 3
	s_add_u32 s20, s20, s93
	s_movk_i32 s23, 1024
	v_mbcnt_hi_u32_b32 v0, -1, v212
	v_and_b32_e32 v0, 63, v0
	v_lshrrev_b32_e32 v1, 3, v0
	v_and_b32_e32 v2, 7, v0
	s_lshl_b32 s25, s93, 14
	v_mul_u32_u24_e32 v3, 0x84, v1
	v_mul_u32_u24_e32 v4, 0x420, v2
	v_lshlrev_b32_e32 v2, 4, v2
	v_add3_u32 v3, v3, v2, s25
	v_lshl_add_u32 v4, v1, 2, v4
	v_add_u32_e32 v4, s25, v4
	v_and_b32_e32 v7, 4, v1
	v_and_b32_e32 v5, 3, v1
	v_lshl_add_u32 v7, v7, 1, v5
	v_readlane_b32 s62, v244, 21
	v_readlane_b32 s63, v244, 22
	s_add_u32 s64, s76, 0x8989000
	s_addc_u32 s65, s77, 0
	s_cmp_ge_u32 s20, 1024
	s_cbranch_scc1 .Ltt2_1_done
	s_sub_u32 s25, s20, -3072
	s_lshr_b32 s27, s25, 6
	s_and_b32 s31, s25, 63
	s_mul_i32 s35, s27, 0x80000
	s_lshl_b32 s41, s31, 7
	s_add_u32 s35, s35, s41
	s_add_u32 s0, s62, s35
	s_addc_u32 s1, s63, 0
	s_mul_i32 s35, s31, 0x80000
	s_lshl_b32 s41, s27, 7
	s_add_u32 s35, s35, s41
	s_add_u32 s2, s64, s35
	s_addc_u32 s3, s65, 0
	s_mov_b32 s5, 0x2000
	s_mov_b32 s6, 0x10000
	s_mov_b32 s7, 0x4000
.Ltt2_1_r1_e:
	v_mad_u32_u24 v5, v1, s5, v2
	global_load_dwordx4 v[8:11], v5, s[0:1] nt
	s_add_u32 s0, s0, s6
	s_addc_u32 s1, s1, 0
	global_load_dwordx4 v[12:15], v5, s[0:1] nt
	s_add_u32 s0, s0, s6
	s_addc_u32 s1, s1, 0
	global_load_dwordx4 v[16:19], v5, s[0:1] nt
	s_add_u32 s0, s0, s6
	s_addc_u32 s1, s1, 0
	global_load_dwordx4 v[20:23], v5, s[0:1] nt
	s_add_u32 s0, s0, s6
	s_addc_u32 s1, s1, 0
	global_load_dwordx4 v[24:27], v5, s[0:1] nt
	s_add_u32 s0, s0, s6
	s_addc_u32 s1, s1, 0
	global_load_dwordx4 v[28:31], v5, s[0:1] nt
	s_add_u32 s0, s0, s6
	s_addc_u32 s1, s1, 0
	global_load_dwordx4 v[32:35], v5, s[0:1] nt
	s_add_u32 s0, s0, s6
	s_addc_u32 s1, s1, 0
	global_load_dwordx4 v[36:39], v5, s[0:1] nt
	s_add_u32 s0, s0, s6
	s_addc_u32 s1, s1, 0
	s_add_u32 s20, s20, s23
	s_cmp_ge_u32 s20, 1024
	s_cbranch_scc1 .Ltt2_1_dr1
	s_sub_u32 s25, s20, -3072
	s_lshr_b32 s27, s25, 6
	s_and_b32 s31, s25, 63
	s_mul_i32 s35, s27, 0x80000
	s_lshl_b32 s41, s31, 7
	s_add_u32 s35, s35, s41
	s_add_u32 s0, s62, s35
	s_addc_u32 s1, s63, 0
	s_mul_i32 s35, s31, 0x80000
	s_lshl_b32 s41, s27, 7
	s_add_u32 s35, s35, s41
	s_add_u32 s10, s64, s35
	s_addc_u32 s11, s65, 0
	s_mov_b32 s5, 0x2000
	s_mov_b32 s6, 0x10000
	s_mov_b32 s47, 0x4000
.Ltt2_1_r2_e:
	v_mad_u32_u24 v5, v1, s5, v2
	global_load_dwordx4 v[40:43], v5, s[0:1] nt
	s_add_u32 s0, s0, s6
	s_addc_u32 s1, s1, 0
	global_load_dwordx4 v[44:47], v5, s[0:1] nt
	s_add_u32 s0, s0, s6
	s_addc_u32 s1, s1, 0
	global_load_dwordx4 v[48:51], v5, s[0:1] nt
	s_add_u32 s0, s0, s6
	s_addc_u32 s1, s1, 0
	global_load_dwordx4 v[52:55], v5, s[0:1] nt
	s_add_u32 s0, s0, s6
	s_addc_u32 s1, s1, 0
	global_load_dwordx4 v[56:59], v5, s[0:1] nt
	s_add_u32 s0, s0, s6
	s_addc_u32 s1, s1, 0
	global_load_dwordx4 v[60:63], v5, s[0:1] nt
	s_add_u32 s0, s0, s6
	s_addc_u32 s1, s1, 0
	global_load_dwordx4 v[64:67], v5, s[0:1] nt
	s_add_u32 s0, s0, s6
	s_addc_u32 s1, s1, 0
	global_load_dwordx4 v[68:71], v5, s[0:1] nt
	s_add_u32 s0, s0, s6
	s_addc_u32 s1, s1, 0
	s_add_u32 s20, s20, s23
	s_cmp_ge_u32 s20, 1024
	s_cbranch_scc1 .Ltt2_1_dr2
	s_sub_u32 s25, s20, -3072
	s_lshr_b32 s27, s25, 6
	s_and_b32 s31, s25, 63
	s_mul_i32 s35, s27, 0x80000
	s_lshl_b32 s41, s31, 7
	s_add_u32 s35, s35, s41
	s_add_u32 s0, s62, s35
	s_addc_u32 s1, s63, 0
	s_mul_i32 s35, s31, 0x80000
	s_lshl_b32 s41, s27, 7
	s_add_u32 s35, s35, s41
	s_add_u32 s42, s64, s35
	s_addc_u32 s43, s65, 0
	s_mov_b32 s5, 0x2000
	s_mov_b32 s6, 0x10000
	s_mov_b32 s44, 0x4000
.Ltt2_1_r3_e:
	v_mad_u32_u24 v5, v1, s5, v2
	global_load_dwordx4 v[72:75], v5, s[0:1] nt
	s_add_u32 s0, s0, s6
	s_addc_u32 s1, s1, 0
	global_load_dwordx4 v[76:79], v5, s[0:1] nt
	s_add_u32 s0, s0, s6
	s_addc_u32 s1, s1, 0
	global_load_dwordx4 v[80:83], v5, s[0:1] nt
	s_add_u32 s0, s0, s6
	s_addc_u32 s1, s1, 0
	global_load_dwordx4 v[84:87], v5, s[0:1] nt
	s_add_u32 s0, s0, s6
	s_addc_u32 s1, s1, 0
	global_load_dwordx4 v[88:91], v5, s[0:1] nt
	s_add_u32 s0, s0, s6
	s_addc_u32 s1, s1, 0
	global_load_dwordx4 v[92:95], v5, s[0:1] nt
	s_add_u32 s0, s0, s6
	s_addc_u32 s1, s1, 0
	global_load_dwordx4 v[96:99], v5, s[0:1] nt
	s_add_u32 s0, s0, s6
	s_addc_u32 s1, s1, 0
	global_load_dwordx4 v[100:103], v5, s[0:1] nt
	s_add_u32 s0, s0, s6
	s_addc_u32 s1, s1, 0
	s_add_u32 s20, s20, s23
	s_waitcnt vmcnt(16)
	ds_write_b32 v3, v8 offset:0
	ds_write_b32 v3, v9 offset:4
	ds_write_b32 v3, v10 offset:8
	ds_write_b32 v3, v11 offset:12
	ds_write_b32 v3, v12 offset:1056
	ds_write_b32 v3, v13 offset:1060
	ds_write_b32 v3, v14 offset:1064
	ds_write_b32 v3, v15 offset:1068
	ds_write_b32 v3, v16 offset:2112
	ds_write_b32 v3, v17 offset:2116
	ds_write_b32 v3, v18 offset:2120
	ds_write_b32 v3, v19 offset:2124
	ds_write_b32 v3, v20 offset:3168
	ds_write_b32 v3, v21 offset:3172
	ds_write_b32 v3, v22 offset:3176
	ds_write_b32 v3, v23 offset:3180
	ds_write_b32 v3, v24 offset:4224
	ds_write_b32 v3, v25 offset:4228
	ds_write_b32 v3, v26 offset:4232
	ds_write_b32 v3, v27 offset:4236
	ds_write_b32 v3, v28 offset:5280
	ds_write_b32 v3, v29 offset:5284
	ds_write_b32 v3, v30 offset:5288
	ds_write_b32 v3, v31 offset:5292
	ds_write_b32 v3, v32 offset:6336
	ds_write_b32 v3, v33 offset:6340
	ds_write_b32 v3, v34 offset:6344
	ds_write_b32 v3, v35 offset:6348
	ds_write_b32 v3, v36 offset:7392
	ds_write_b32 v3, v37 offset:7396
	ds_write_b32 v3, v38 offset:7400
	ds_write_b32 v3, v39 offset:7404
	s_mov_b32 s32, s2
	s_mov_b32 s33, s3
	s_lshl_b32 s49, s7, 3
	v_mad_u32_u24 v6, v1, s7, v2
	s_waitcnt lgkmcnt(0)
	ds_read_b32 v104, v4 offset:0
	ds_read_b32 v105, v4 offset:132
	ds_read_b32 v106, v4 offset:264
	ds_read_b32 v107, v4 offset:396
	ds_read_b32 v108, v4 offset:528
	ds_read_b32 v109, v4 offset:660
	ds_read_b32 v110, v4 offset:792
	ds_read_b32 v111, v4 offset:924
	ds_read_b32 v112, v4 offset:32
	ds_read_b32 v113, v4 offset:164
	ds_read_b32 v114, v4 offset:296
	ds_read_b32 v115, v4 offset:428
	ds_read_b32 v116, v4 offset:560
	ds_read_b32 v117, v4 offset:692
	ds_read_b32 v118, v4 offset:824
	ds_read_b32 v119, v4 offset:956
	s_waitcnt lgkmcnt(8)
	v_cvt_pk_bf16_f32 v136, v104, v105
	v_cvt_pk_bf16_f32 v137, v106, v107
	v_cvt_pk_bf16_f32 v138, v108, v109
	v_cvt_pk_bf16_f32 v139, v110, v111
	global_store_dwordx4 v6, v[136:139], s[32:33] nt
	s_add_u32 s32, s32, s49
	s_addc_u32 s33, s33, 0
	ds_read_b32 v120, v4 offset:64
	ds_read_b32 v121, v4 offset:196
	ds_read_b32 v122, v4 offset:328
	ds_read_b32 v123, v4 offset:460
	ds_read_b32 v124, v4 offset:592
	ds_read_b32 v125, v4 offset:724
	ds_read_b32 v126, v4 offset:856
	ds_read_b32 v127, v4 offset:988
	s_waitcnt lgkmcnt(8)
	v_cvt_pk_bf16_f32 v140, v112, v113
	v_cvt_pk_bf16_f32 v141, v114, v115
	v_cvt_pk_bf16_f32 v142, v116, v117
	v_cvt_pk_bf16_f32 v143, v118, v119
	global_store_dwordx4 v6, v[140:143], s[32:33] nt
	s_add_u32 s32, s32, s49
	s_addc_u32 s33, s33, 0
	ds_read_b32 v128, v4 offset:96
	ds_read_b32 v129, v4 offset:228
	ds_read_b32 v130, v4 offset:360
	ds_read_b32 v131, v4 offset:492
	ds_read_b32 v132, v4 offset:624
	ds_read_b32 v133, v4 offset:756
	ds_read_b32 v134, v4 offset:888
	ds_read_b32 v135, v4 offset:1020
	s_waitcnt lgkmcnt(8)
	v_cvt_pk_bf16_f32 v136, v120, v121
	v_cvt_pk_bf16_f32 v137, v122, v123
	v_cvt_pk_bf16_f32 v138, v124, v125
	v_cvt_pk_bf16_f32 v139, v126, v127
	global_store_dwordx4 v6, v[136:139], s[32:33] nt
	s_add_u32 s32, s32, s49
	s_addc_u32 s33, s33, 0
	s_waitcnt lgkmcnt(0)
	v_cvt_pk_bf16_f32 v140, v128, v129
	v_cvt_pk_bf16_f32 v141, v130, v131
	v_cvt_pk_bf16_f32 v142, v132, v133
	v_cvt_pk_bf16_f32 v143, v134, v135
	global_store_dwordx4 v6, v[140:143], s[32:33] nt
	s_add_u32 s32, s32, s49
	s_addc_u32 s33, s33, 0
	s_cmp_ge_u32 s20, 1024
	s_cbranch_scc1 .Ltt2_1_dr3
	s_sub_u32 s25, s20, -3072
	s_lshr_b32 s27, s25, 6
	s_and_b32 s31, s25, 63
	s_mul_i32 s35, s27, 0x80000
	s_lshl_b32 s41, s31, 7
	s_add_u32 s35, s35, s41
	s_add_u32 s0, s62, s35
	s_addc_u32 s1, s63, 0
	s_mul_i32 s35, s31, 0x80000
	s_lshl_b32 s41, s27, 7
	s_add_u32 s35, s35, s41
	s_add_u32 s2, s64, s35
	s_addc_u32 s3, s65, 0
	s_mov_b32 s5, 0x2000
	s_mov_b32 s6, 0x10000
	s_mov_b32 s7, 0x4000

.Ltt2_1_loop:
	s_cmp_ge_u32 s20, 1024
	s_cbranch_scc1 .Ltt2_1_dr4
	s_sub_u32 s25, s20, -3072
	s_lshr_b32 s27, s25, 6
	s_and_b32 s31, s25, 63
	s_mul_i32 s35, s27, 0x80000
	s_lshl_b32 s41, s31, 7
	s_add_u32 s35, s35, s41
	s_add_u32 s0, s62, s35
	s_addc_u32 s1, s63, 0
	s_mul_i32 s35, s31, 0x80000
	s_lshl_b32 s41, s27, 7
	s_add_u32 s35, s35, s41
	s_add_u32 s10, s64, s35
	s_addc_u32 s11, s65, 0
	s_mov_b32 s5, 0x2000
	s_mov_b32 s6, 0x10000
	s_mov_b32 s47, 0x4000
.Ltt2_1_r5_e:
	v_mad_u32_u24 v5, v1, s5, v2
	global_load_dwordx4 v[40:43], v5, s[0:1] nt
	s_add_u32 s0, s0, s6
	s_addc_u32 s1, s1, 0
	global_load_dwordx4 v[44:47], v5, s[0:1] nt
	s_add_u32 s0, s0, s6
	s_addc_u32 s1, s1, 0
	global_load_dwordx4 v[48:51], v5, s[0:1] nt
	s_add_u32 s0, s0, s6
	s_addc_u32 s1, s1, 0
	global_load_dwordx4 v[52:55], v5, s[0:1] nt
	s_add_u32 s0, s0, s6
	s_addc_u32 s1, s1, 0
	global_load_dwordx4 v[56:59], v5, s[0:1] nt
	s_add_u32 s0, s0, s6
	s_addc_u32 s1, s1, 0
	global_load_dwordx4 v[60:63], v5, s[0:1] nt
	s_add_u32 s0, s0, s6
	s_addc_u32 s1, s1, 0
	global_load_dwordx4 v[64:67], v5, s[0:1] nt
	s_add_u32 s0, s0, s6
	s_addc_u32 s1, s1, 0
	global_load_dwordx4 v[68:71], v5, s[0:1] nt
	s_add_u32 s0, s0, s6
	s_addc_u32 s1, s1, 0
	s_add_u32 s20, s20, s23
	s_waitcnt vmcnt(24)
	ds_write_b32 v3, v72 offset:0
	ds_write_b32 v3, v73 offset:4
	ds_write_b32 v3, v74 offset:8
	ds_write_b32 v3, v75 offset:12
	ds_write_b32 v3, v76 offset:1056
	ds_write_b32 v3, v77 offset:1060
	ds_write_b32 v3, v78 offset:1064
	ds_write_b32 v3, v79 offset:1068
	ds_write_b32 v3, v80 offset:2112
	ds_write_b32 v3, v81 offset:2116
	ds_write_b32 v3, v82 offset:2120
	ds_write_b32 v3, v83 offset:2124
	ds_write_b32 v3, v84 offset:3168
	ds_write_b32 v3, v85 offset:3172
	ds_write_b32 v3, v86 offset:3176
	ds_write_b32 v3, v87 offset:3180
	ds_write_b32 v3, v88 offset:4224
	ds_write_b32 v3, v89 offset:4228
	ds_write_b32 v3, v90 offset:4232
	ds_write_b32 v3, v91 offset:4236
	ds_write_b32 v3, v92 offset:5280
	ds_write_b32 v3, v93 offset:5284
	ds_write_b32 v3, v94 offset:5288
	ds_write_b32 v3, v95 offset:5292
	ds_write_b32 v3, v96 offset:6336
	ds_write_b32 v3, v97 offset:6340
	ds_write_b32 v3, v98 offset:6344
	ds_write_b32 v3, v99 offset:6348
	ds_write_b32 v3, v100 offset:7392
	ds_write_b32 v3, v101 offset:7396
	ds_write_b32 v3, v102 offset:7400
	ds_write_b32 v3, v103 offset:7404
	s_mov_b32 s32, s42
	s_mov_b32 s33, s43
	s_lshl_b32 s49, s44, 3
	v_mad_u32_u24 v6, v1, s44, v2
	s_waitcnt lgkmcnt(0)
	ds_read_b32 v104, v4 offset:0
	ds_read_b32 v105, v4 offset:132
	ds_read_b32 v106, v4 offset:264
	ds_read_b32 v107, v4 offset:396
	ds_read_b32 v108, v4 offset:528
	ds_read_b32 v109, v4 offset:660
	ds_read_b32 v110, v4 offset:792
	ds_read_b32 v111, v4 offset:924
	ds_read_b32 v112, v4 offset:32
	ds_read_b32 v113, v4 offset:164
	ds_read_b32 v114, v4 offset:296
	ds_read_b32 v115, v4 offset:428
	ds_read_b32 v116, v4 offset:560
	ds_read_b32 v117, v4 offset:692
	ds_read_b32 v118, v4 offset:824
	ds_read_b32 v119, v4 offset:956
	s_waitcnt lgkmcnt(8)
	v_cvt_pk_bf16_f32 v136, v104, v105
	v_cvt_pk_bf16_f32 v137, v106, v107
	v_cvt_pk_bf16_f32 v138, v108, v109
	v_cvt_pk_bf16_f32 v139, v110, v111
	global_store_dwordx4 v6, v[136:139], s[32:33] nt
	s_add_u32 s32, s32, s49
	s_addc_u32 s33, s33, 0
	ds_read_b32 v120, v4 offset:64
	ds_read_b32 v121, v4 offset:196
	ds_read_b32 v122, v4 offset:328
	ds_read_b32 v123, v4 offset:460
	ds_read_b32 v124, v4 offset:592
	ds_read_b32 v125, v4 offset:724
	ds_read_b32 v126, v4 offset:856
	ds_read_b32 v127, v4 offset:988
	s_waitcnt lgkmcnt(8)
	v_cvt_pk_bf16_f32 v140, v112, v113
	v_cvt_pk_bf16_f32 v141, v114, v115
	v_cvt_pk_bf16_f32 v142, v116, v117
	v_cvt_pk_bf16_f32 v143, v118, v119
	global_store_dwordx4 v6, v[140:143], s[32:33] nt
	s_add_u32 s32, s32, s49
	s_addc_u32 s33, s33, 0
	ds_read_b32 v128, v4 offset:96
	ds_read_b32 v129, v4 offset:228
	ds_read_b32 v130, v4 offset:360
	ds_read_b32 v131, v4 offset:492
	ds_read_b32 v132, v4 offset:624
	ds_read_b32 v133, v4 offset:756
	ds_read_b32 v134, v4 offset:888
	ds_read_b32 v135, v4 offset:1020
	s_waitcnt lgkmcnt(8)
	v_cvt_pk_bf16_f32 v136, v120, v121
	v_cvt_pk_bf16_f32 v137, v122, v123
	v_cvt_pk_bf16_f32 v138, v124, v125
	v_cvt_pk_bf16_f32 v139, v126, v127
	global_store_dwordx4 v6, v[136:139], s[32:33] nt
	s_add_u32 s32, s32, s49
	s_addc_u32 s33, s33, 0
	s_waitcnt lgkmcnt(0)
	v_cvt_pk_bf16_f32 v140, v128, v129
	v_cvt_pk_bf16_f32 v141, v130, v131
	v_cvt_pk_bf16_f32 v142, v132, v133
	v_cvt_pk_bf16_f32 v143, v134, v135
	global_store_dwordx4 v6, v[140:143], s[32:33] nt
	s_add_u32 s32, s32, s49
	s_addc_u32 s33, s33, 0
	s_cmp_ge_u32 s20, 1024
	s_cbranch_scc1 .Ltt2_1_dr5
	s_sub_u32 s25, s20, -3072
	s_lshr_b32 s27, s25, 6
	s_and_b32 s31, s25, 63
	s_mul_i32 s35, s27, 0x80000
	s_lshl_b32 s41, s31, 7
	s_add_u32 s35, s35, s41
	s_add_u32 s0, s62, s35
	s_addc_u32 s1, s63, 0
	s_mul_i32 s35, s31, 0x80000
	s_lshl_b32 s41, s27, 7
	s_add_u32 s35, s35, s41
	s_add_u32 s42, s64, s35
	s_addc_u32 s43, s65, 0
	s_mov_b32 s5, 0x2000
	s_mov_b32 s6, 0x10000
	s_mov_b32 s44, 0x4000
.Ltt2_1_r6_e:
	v_mad_u32_u24 v5, v1, s5, v2
	global_load_dwordx4 v[72:75], v5, s[0:1] nt
	s_add_u32 s0, s0, s6
	s_addc_u32 s1, s1, 0
	global_load_dwordx4 v[76:79], v5, s[0:1] nt
	s_add_u32 s0, s0, s6
	s_addc_u32 s1, s1, 0
	global_load_dwordx4 v[80:83], v5, s[0:1] nt
	s_add_u32 s0, s0, s6
	s_addc_u32 s1, s1, 0
	global_load_dwordx4 v[84:87], v5, s[0:1] nt
	s_add_u32 s0, s0, s6
	s_addc_u32 s1, s1, 0
	global_load_dwordx4 v[88:91], v5, s[0:1] nt
	s_add_u32 s0, s0, s6
	s_addc_u32 s1, s1, 0
	global_load_dwordx4 v[92:95], v5, s[0:1] nt
	s_add_u32 s0, s0, s6
	s_addc_u32 s1, s1, 0
	global_load_dwordx4 v[96:99], v5, s[0:1] nt
	s_add_u32 s0, s0, s6
	s_addc_u32 s1, s1, 0
	global_load_dwordx4 v[100:103], v5, s[0:1] nt
	s_add_u32 s0, s0, s6
	s_addc_u32 s1, s1, 0
	s_add_u32 s20, s20, s23
	s_waitcnt vmcnt(24)
	ds_write_b32 v3, v8 offset:0
	ds_write_b32 v3, v9 offset:4
	ds_write_b32 v3, v10 offset:8
	ds_write_b32 v3, v11 offset:12
	ds_write_b32 v3, v12 offset:1056
	ds_write_b32 v3, v13 offset:1060
	ds_write_b32 v3, v14 offset:1064
	ds_write_b32 v3, v15 offset:1068
	ds_write_b32 v3, v16 offset:2112
	ds_write_b32 v3, v17 offset:2116
	ds_write_b32 v3, v18 offset:2120
	ds_write_b32 v3, v19 offset:2124
	ds_write_b32 v3, v20 offset:3168
	ds_write_b32 v3, v21 offset:3172
	ds_write_b32 v3, v22 offset:3176
	ds_write_b32 v3, v23 offset:3180
	ds_write_b32 v3, v24 offset:4224
	ds_write_b32 v3, v25 offset:4228
	ds_write_b32 v3, v26 offset:4232
	ds_write_b32 v3, v27 offset:4236
	ds_write_b32 v3, v28 offset:5280
	ds_write_b32 v3, v29 offset:5284
	ds_write_b32 v3, v30 offset:5288
	ds_write_b32 v3, v31 offset:5292
	ds_write_b32 v3, v32 offset:6336
	ds_write_b32 v3, v33 offset:6340
	ds_write_b32 v3, v34 offset:6344
	ds_write_b32 v3, v35 offset:6348
	ds_write_b32 v3, v36 offset:7392
	ds_write_b32 v3, v37 offset:7396
	ds_write_b32 v3, v38 offset:7400
	ds_write_b32 v3, v39 offset:7404
	s_mov_b32 s32, s2
	s_mov_b32 s33, s3
	s_lshl_b32 s49, s7, 3
	v_mad_u32_u24 v6, v1, s7, v2
	s_waitcnt lgkmcnt(0)
	ds_read_b32 v104, v4 offset:0
	ds_read_b32 v105, v4 offset:132
	ds_read_b32 v106, v4 offset:264
	ds_read_b32 v107, v4 offset:396
	ds_read_b32 v108, v4 offset:528
	ds_read_b32 v109, v4 offset:660
	ds_read_b32 v110, v4 offset:792
	ds_read_b32 v111, v4 offset:924
	ds_read_b32 v112, v4 offset:32
	ds_read_b32 v113, v4 offset:164
	ds_read_b32 v114, v4 offset:296
	ds_read_b32 v115, v4 offset:428
	ds_read_b32 v116, v4 offset:560
	ds_read_b32 v117, v4 offset:692
	ds_read_b32 v118, v4 offset:824
	ds_read_b32 v119, v4 offset:956
	s_waitcnt lgkmcnt(8)
	v_cvt_pk_bf16_f32 v136, v104, v105
	v_cvt_pk_bf16_f32 v137, v106, v107
	v_cvt_pk_bf16_f32 v138, v108, v109
	v_cvt_pk_bf16_f32 v139, v110, v111
	global_store_dwordx4 v6, v[136:139], s[32:33] nt
	s_add_u32 s32, s32, s49
	s_addc_u32 s33, s33, 0
	ds_read_b32 v120, v4 offset:64
	ds_read_b32 v121, v4 offset:196
	ds_read_b32 v122, v4 offset:328
	ds_read_b32 v123, v4 offset:460
	ds_read_b32 v124, v4 offset:592
	ds_read_b32 v125, v4 offset:724
	ds_read_b32 v126, v4 offset:856
	ds_read_b32 v127, v4 offset:988
	s_waitcnt lgkmcnt(8)
	v_cvt_pk_bf16_f32 v140, v112, v113
	v_cvt_pk_bf16_f32 v141, v114, v115
	v_cvt_pk_bf16_f32 v142, v116, v117
	v_cvt_pk_bf16_f32 v143, v118, v119
	global_store_dwordx4 v6, v[140:143], s[32:33] nt
	s_add_u32 s32, s32, s49
	s_addc_u32 s33, s33, 0
	ds_read_b32 v128, v4 offset:96
	ds_read_b32 v129, v4 offset:228
	ds_read_b32 v130, v4 offset:360
	ds_read_b32 v131, v4 offset:492
	ds_read_b32 v132, v4 offset:624
	ds_read_b32 v133, v4 offset:756
	ds_read_b32 v134, v4 offset:888
	ds_read_b32 v135, v4 offset:1020
	s_waitcnt lgkmcnt(8)
	v_cvt_pk_bf16_f32 v136, v120, v121
	v_cvt_pk_bf16_f32 v137, v122, v123
	v_cvt_pk_bf16_f32 v138, v124, v125
	v_cvt_pk_bf16_f32 v139, v126, v127
	global_store_dwordx4 v6, v[136:139], s[32:33] nt
	s_add_u32 s32, s32, s49
	s_addc_u32 s33, s33, 0
	s_waitcnt lgkmcnt(0)
	v_cvt_pk_bf16_f32 v140, v128, v129
	v_cvt_pk_bf16_f32 v141, v130, v131
	v_cvt_pk_bf16_f32 v142, v132, v133
	v_cvt_pk_bf16_f32 v143, v134, v135
	global_store_dwordx4 v6, v[140:143], s[32:33] nt
	s_add_u32 s32, s32, s49
	s_addc_u32 s33, s33, 0
	s_cmp_ge_u32 s20, 1024
	s_cbranch_scc1 .Ltt2_1_dr6
	s_sub_u32 s25, s20, -3072
	s_lshr_b32 s27, s25, 6
	s_and_b32 s31, s25, 63
	s_mul_i32 s35, s27, 0x80000
	s_lshl_b32 s41, s31, 7
	s_add_u32 s35, s35, s41
	s_add_u32 s0, s62, s35
	s_addc_u32 s1, s63, 0
	s_mul_i32 s35, s31, 0x80000
	s_lshl_b32 s41, s27, 7
	s_add_u32 s35, s35, s41
	s_add_u32 s2, s64, s35
	s_addc_u32 s3, s65, 0
	s_mov_b32 s5, 0x2000
	s_mov_b32 s6, 0x10000
	s_mov_b32 s7, 0x4000

.LBB0_832:
	s_waitcnt vmcnt(0)
	s_barrier
	s_cmp_lg_u32 s87, 0x100
	s_cbranch_scc1 .Ltt7_0_done
	s_cmp_lt_u32 s96, 128
	s_cbranch_scc1 .Ltt7_0_done
	s_cmp_ge_u32 s96, 256
	s_cbranch_scc1 .Ltt7_0_done
	s_sub_u32 s20, s96, 128
	s_lshl_b32 s20, s20, 3
	s_add_u32 s20, s20, s93
	s_movk_i32 s23, 1024
	v_mbcnt_hi_u32_b32 v0, -1, v212
	v_and_b32_e32 v0, 63, v0
	v_lshrrev_b32_e32 v1, 3, v0
	v_and_b32_e32 v2, 7, v0
	s_lshl_b32 s25, s93, 14
	v_mul_u32_u24_e32 v3, 0x84, v1
	v_mul_u32_u24_e32 v4, 0x420, v2
	v_lshlrev_b32_e32 v2, 4, v2
	v_add3_u32 v3, v3, v2, s25
	v_lshl_add_u32 v4, v1, 2, v4
	v_add_u32_e32 v4, s25, v4
	v_and_b32_e32 v7, 4, v1
	v_and_b32_e32 v5, 3, v1
	v_lshl_add_u32 v7, v7, 1, v5
	v_readlane_b32 s62, v244, 21
	v_readlane_b32 s63, v244, 22
	s_add_u32 s64, s76, 0x8989000
	s_addc_u32 s65, s77, 0
	v_readlane_b32 s66, v245, 0
	v_readlane_b32 s67, v245, 1
	s_add_u32 s68, s76, 0x6989000
	s_addc_u32 s69, s77, 0
	s_nop 0
	s_add_u32 s66, s66, 0x4000000
	s_addc_u32 s67, s67, 0
	s_cmp_ge_u32 s20, 11264
	s_cbranch_scc1 .Ltt7_0_done
	s_cmp_lt_u32 s20, 4096
	s_cbranch_scc1 .Ltt7_0_r1_s0
	s_sub_u32 s25, s20, 4096
	s_lshr_b32 s27, s25, 8
	s_and_b32 s31, s25, 255
	s_mul_i32 s35, s27, 0x200000
	s_lshl_b32 s41, s31, 7
	s_add_u32 s35, s35, s41
	s_add_u32 s0, s66, s35
	s_addc_u32 s1, s67, 0
	s_mul_i32 s35, s31, 0x20000
	s_lshl_b32 s41, s27, 7
	s_add_u32 s35, s35, s41
	s_add_u32 s2, s68, s35
	s_addc_u32 s3, s69, 0
	s_mov_b32 s5, 0x8000
	s_mov_b32 s6, 0x40000
	s_mov_b32 s7, 0x1000
	s_branch .Ltt7_0_r1_e

.Ltt7_0_r1_e:
	v_mad_u32_u24 v5, v1, s5, v2
	global_load_dwordx4 v[8:11], v5, s[0:1] nt
	s_add_u32 s0, s0, s6
	s_addc_u32 s1, s1, 0
	global_load_dwordx4 v[12:15], v5, s[0:1] nt
	s_add_u32 s0, s0, s6
	s_addc_u32 s1, s1, 0
	global_load_dwordx4 v[16:19], v5, s[0:1] nt
	s_add_u32 s0, s0, s6
	s_addc_u32 s1, s1, 0
	global_load_dwordx4 v[20:23], v5, s[0:1] nt
	s_add_u32 s0, s0, s6
	s_addc_u32 s1, s1, 0
	global_load_dwordx4 v[24:27], v5, s[0:1] nt
	s_add_u32 s0, s0, s6
	s_addc_u32 s1, s1, 0
	global_load_dwordx4 v[28:31], v5, s[0:1] nt
	s_add_u32 s0, s0, s6
	s_addc_u32 s1, s1, 0
	global_load_dwordx4 v[32:35], v5, s[0:1] nt
	s_add_u32 s0, s0, s6
	s_addc_u32 s1, s1, 0
	global_load_dwordx4 v[36:39], v5, s[0:1] nt
	s_add_u32 s0, s0, s6
	s_addc_u32 s1, s1, 0
	s_add_u32 s20, s20, s23
	s_cmp_ge_u32 s20, 11264
	s_cbranch_scc1 .Ltt7_0_dr1
	s_cmp_lt_u32 s20, 4096
	s_cbranch_scc1 .Ltt7_0_r2_s0
	s_sub_u32 s25, s20, 4096
	s_lshr_b32 s27, s25, 8
	s_and_b32 s31, s25, 255
	s_mul_i32 s35, s27, 0x200000
	s_lshl_b32 s41, s31, 7
	s_add_u32 s35, s35, s41
	s_add_u32 s0, s66, s35
	s_addc_u32 s1, s67, 0
	s_mul_i32 s35, s31, 0x20000
	s_lshl_b32 s41, s27, 7
	s_add_u32 s35, s35, s41
	s_add_u32 s10, s68, s35
	s_addc_u32 s11, s69, 0
	s_mov_b32 s5, 0x8000
	s_mov_b32 s6, 0x40000
	s_mov_b32 s47, 0x1000
	s_branch .Ltt7_0_r2_e

.Ltt7_0_r2_e:
	v_mad_u32_u24 v5, v1, s5, v2
	global_load_dwordx4 v[40:43], v5, s[0:1] nt
	s_add_u32 s0, s0, s6
	s_addc_u32 s1, s1, 0
	global_load_dwordx4 v[44:47], v5, s[0:1] nt
	s_add_u32 s0, s0, s6
	s_addc_u32 s1, s1, 0
	global_load_dwordx4 v[48:51], v5, s[0:1] nt
	s_add_u32 s0, s0, s6
	s_addc_u32 s1, s1, 0
	global_load_dwordx4 v[52:55], v5, s[0:1] nt
	s_add_u32 s0, s0, s6
	s_addc_u32 s1, s1, 0
	global_load_dwordx4 v[56:59], v5, s[0:1] nt
	s_add_u32 s0, s0, s6
	s_addc_u32 s1, s1, 0
	global_load_dwordx4 v[60:63], v5, s[0:1] nt
	s_add_u32 s0, s0, s6
	s_addc_u32 s1, s1, 0
	global_load_dwordx4 v[64:67], v5, s[0:1] nt
	s_add_u32 s0, s0, s6
	s_addc_u32 s1, s1, 0
	global_load_dwordx4 v[68:71], v5, s[0:1] nt
	s_add_u32 s0, s0, s6
	s_addc_u32 s1, s1, 0
	s_add_u32 s20, s20, s23
	s_cmp_ge_u32 s20, 11264
	s_cbranch_scc1 .Ltt7_0_dr2
	s_cmp_lt_u32 s20, 4096
	s_cbranch_scc1 .Ltt7_0_r3_s0
	s_sub_u32 s25, s20, 4096
	s_lshr_b32 s27, s25, 8
	s_and_b32 s31, s25, 255
	s_mul_i32 s35, s27, 0x200000
	s_lshl_b32 s41, s31, 7
	s_add_u32 s35, s35, s41
	s_add_u32 s0, s66, s35
	s_addc_u32 s1, s67, 0
	s_mul_i32 s35, s31, 0x20000
	s_lshl_b32 s41, s27, 7
	s_add_u32 s35, s35, s41
	s_add_u32 s42, s68, s35
	s_addc_u32 s43, s69, 0
	s_mov_b32 s5, 0x8000
	s_mov_b32 s6, 0x40000
	s_mov_b32 s44, 0x1000
	s_branch .Ltt7_0_r3_e

.Ltt7_0_r3_e:
	v_mad_u32_u24 v5, v1, s5, v2
	global_load_dwordx4 v[72:75], v5, s[0:1] nt
	s_add_u32 s0, s0, s6
	s_addc_u32 s1, s1, 0
	global_load_dwordx4 v[76:79], v5, s[0:1] nt
	s_add_u32 s0, s0, s6
	s_addc_u32 s1, s1, 0
	global_load_dwordx4 v[80:83], v5, s[0:1] nt
	s_add_u32 s0, s0, s6
	s_addc_u32 s1, s1, 0
	global_load_dwordx4 v[84:87], v5, s[0:1] nt
	s_add_u32 s0, s0, s6
	s_addc_u32 s1, s1, 0
	global_load_dwordx4 v[88:91], v5, s[0:1] nt
	s_add_u32 s0, s0, s6
	s_addc_u32 s1, s1, 0
	global_load_dwordx4 v[92:95], v5, s[0:1] nt
	s_add_u32 s0, s0, s6
	s_addc_u32 s1, s1, 0
	global_load_dwordx4 v[96:99], v5, s[0:1] nt
	s_add_u32 s0, s0, s6
	s_addc_u32 s1, s1, 0
	global_load_dwordx4 v[100:103], v5, s[0:1] nt
	s_add_u32 s0, s0, s6
	s_addc_u32 s1, s1, 0
	s_add_u32 s20, s20, s23
	s_waitcnt vmcnt(16)
	ds_write_b32 v3, v8 offset:0
	ds_write_b32 v3, v9 offset:4
	ds_write_b32 v3, v10 offset:8
	ds_write_b32 v3, v11 offset:12
	ds_write_b32 v3, v12 offset:1056
	ds_write_b32 v3, v13 offset:1060
	ds_write_b32 v3, v14 offset:1064
	ds_write_b32 v3, v15 offset:1068
	ds_write_b32 v3, v16 offset:2112
	ds_write_b32 v3, v17 offset:2116
	ds_write_b32 v3, v18 offset:2120
	ds_write_b32 v3, v19 offset:2124
	ds_write_b32 v3, v20 offset:3168
	ds_write_b32 v3, v21 offset:3172
	ds_write_b32 v3, v22 offset:3176
	ds_write_b32 v3, v23 offset:3180
	ds_write_b32 v3, v24 offset:4224
	ds_write_b32 v3, v25 offset:4228
	ds_write_b32 v3, v26 offset:4232
	ds_write_b32 v3, v27 offset:4236
	ds_write_b32 v3, v28 offset:5280
	ds_write_b32 v3, v29 offset:5284
	ds_write_b32 v3, v30 offset:5288
	ds_write_b32 v3, v31 offset:5292
	ds_write_b32 v3, v32 offset:6336
	ds_write_b32 v3, v33 offset:6340
	ds_write_b32 v3, v34 offset:6344
	ds_write_b32 v3, v35 offset:6348
	ds_write_b32 v3, v36 offset:7392
	ds_write_b32 v3, v37 offset:7396
	ds_write_b32 v3, v38 offset:7400
	ds_write_b32 v3, v39 offset:7404
	s_mov_b32 s32, s2
	s_mov_b32 s33, s3
	s_lshl_b32 s49, s7, 3
	v_mad_u32_u24 v6, v1, s7, v2
	s_waitcnt lgkmcnt(0)
	ds_read_b32 v104, v4 offset:0
	ds_read_b32 v105, v4 offset:132
	ds_read_b32 v106, v4 offset:264
	ds_read_b32 v107, v4 offset:396
	ds_read_b32 v108, v4 offset:528
	ds_read_b32 v109, v4 offset:660
	ds_read_b32 v110, v4 offset:792
	ds_read_b32 v111, v4 offset:924
	ds_read_b32 v112, v4 offset:32
	ds_read_b32 v113, v4 offset:164
	ds_read_b32 v114, v4 offset:296
	ds_read_b32 v115, v4 offset:428
	ds_read_b32 v116, v4 offset:560
	ds_read_b32 v117, v4 offset:692
	ds_read_b32 v118, v4 offset:824
	ds_read_b32 v119, v4 offset:956
	s_waitcnt lgkmcnt(8)
	v_cvt_pk_bf16_f32 v136, v104, v105
	v_cvt_pk_bf16_f32 v137, v106, v107
	v_cvt_pk_bf16_f32 v138, v108, v109
	v_cvt_pk_bf16_f32 v139, v110, v111
	global_store_dwordx4 v6, v[136:139], s[32:33] nt
	s_add_u32 s32, s32, s49
	s_addc_u32 s33, s33, 0
	ds_read_b32 v120, v4 offset:64
	ds_read_b32 v121, v4 offset:196
	ds_read_b32 v122, v4 offset:328
	ds_read_b32 v123, v4 offset:460
	ds_read_b32 v124, v4 offset:592
	ds_read_b32 v125, v4 offset:724
	ds_read_b32 v126, v4 offset:856
	ds_read_b32 v127, v4 offset:988
	s_waitcnt lgkmcnt(8)
	v_cvt_pk_bf16_f32 v140, v112, v113
	v_cvt_pk_bf16_f32 v141, v114, v115
	v_cvt_pk_bf16_f32 v142, v116, v117
	v_cvt_pk_bf16_f32 v143, v118, v119
	global_store_dwordx4 v6, v[140:143], s[32:33] nt
	s_add_u32 s32, s32, s49
	s_addc_u32 s33, s33, 0
	ds_read_b32 v128, v4 offset:96
	ds_read_b32 v129, v4 offset:228
	ds_read_b32 v130, v4 offset:360
	ds_read_b32 v131, v4 offset:492
	ds_read_b32 v132, v4 offset:624
	ds_read_b32 v133, v4 offset:756
	ds_read_b32 v134, v4 offset:888
	ds_read_b32 v135, v4 offset:1020
	s_waitcnt lgkmcnt(8)
	v_cvt_pk_bf16_f32 v136, v120, v121
	v_cvt_pk_bf16_f32 v137, v122, v123
	v_cvt_pk_bf16_f32 v138, v124, v125
	v_cvt_pk_bf16_f32 v139, v126, v127
	global_store_dwordx4 v6, v[136:139], s[32:33] nt
	s_add_u32 s32, s32, s49
	s_addc_u32 s33, s33, 0
	s_waitcnt lgkmcnt(0)
	v_cvt_pk_bf16_f32 v140, v128, v129
	v_cvt_pk_bf16_f32 v141, v130, v131
	v_cvt_pk_bf16_f32 v142, v132, v133
	v_cvt_pk_bf16_f32 v143, v134, v135
	global_store_dwordx4 v6, v[140:143], s[32:33] nt
	s_add_u32 s32, s32, s49
	s_addc_u32 s33, s33, 0
	s_cmp_ge_u32 s20, 11264
	s_cbranch_scc1 .Ltt7_0_dr3
	s_cmp_lt_u32 s20, 4096
	s_cbranch_scc1 .Ltt7_0_r4_s0
	s_sub_u32 s25, s20, 4096
	s_lshr_b32 s27, s25, 8
	s_and_b32 s31, s25, 255
	s_mul_i32 s35, s27, 0x200000
	s_lshl_b32 s41, s31, 7
	s_add_u32 s35, s35, s41
	s_add_u32 s0, s66, s35
	s_addc_u32 s1, s67, 0
	s_mul_i32 s35, s31, 0x20000
	s_lshl_b32 s41, s27, 7
	s_add_u32 s35, s35, s41
	s_add_u32 s2, s68, s35
	s_addc_u32 s3, s69, 0
	s_mov_b32 s5, 0x8000
	s_mov_b32 s6, 0x40000
	s_mov_b32 s7, 0x1000
	s_branch .Ltt7_0_r4_e

.Ltt7_0_loop:
	s_cmp_ge_u32 s20, 11264
	s_cbranch_scc1 .Ltt7_0_dr4
	s_cmp_lt_u32 s20, 4096
	s_cbranch_scc1 .Ltt7_0_r5_s0
	s_sub_u32 s25, s20, 4096
	s_lshr_b32 s27, s25, 8
	s_and_b32 s31, s25, 255
	s_mul_i32 s35, s27, 0x200000
	s_lshl_b32 s41, s31, 7
	s_add_u32 s35, s35, s41
	s_add_u32 s0, s66, s35
	s_addc_u32 s1, s67, 0
	s_mul_i32 s35, s31, 0x20000
	s_lshl_b32 s41, s27, 7
	s_add_u32 s35, s35, s41
	s_add_u32 s10, s68, s35
	s_addc_u32 s11, s69, 0
	s_mov_b32 s5, 0x8000
	s_mov_b32 s6, 0x40000
	s_mov_b32 s47, 0x1000
	s_branch .Ltt7_0_r5_e

.Ltt7_0_r5_e:
	v_mad_u32_u24 v5, v1, s5, v2
	global_load_dwordx4 v[40:43], v5, s[0:1] nt
	s_add_u32 s0, s0, s6
	s_addc_u32 s1, s1, 0
	global_load_dwordx4 v[44:47], v5, s[0:1] nt
	s_add_u32 s0, s0, s6
	s_addc_u32 s1, s1, 0
	global_load_dwordx4 v[48:51], v5, s[0:1] nt
	s_add_u32 s0, s0, s6
	s_addc_u32 s1, s1, 0
	global_load_dwordx4 v[52:55], v5, s[0:1] nt
	s_add_u32 s0, s0, s6
	s_addc_u32 s1, s1, 0
	global_load_dwordx4 v[56:59], v5, s[0:1] nt
	s_add_u32 s0, s0, s6
	s_addc_u32 s1, s1, 0
	global_load_dwordx4 v[60:63], v5, s[0:1] nt
	s_add_u32 s0, s0, s6
	s_addc_u32 s1, s1, 0
	global_load_dwordx4 v[64:67], v5, s[0:1] nt
	s_add_u32 s0, s0, s6
	s_addc_u32 s1, s1, 0
	global_load_dwordx4 v[68:71], v5, s[0:1] nt
	s_add_u32 s0, s0, s6
	s_addc_u32 s1, s1, 0
	s_add_u32 s20, s20, s23
	s_waitcnt vmcnt(24)
	ds_write_b32 v3, v72 offset:0
	ds_write_b32 v3, v73 offset:4
	ds_write_b32 v3, v74 offset:8
	ds_write_b32 v3, v75 offset:12
	ds_write_b32 v3, v76 offset:1056
	ds_write_b32 v3, v77 offset:1060
	ds_write_b32 v3, v78 offset:1064
	ds_write_b32 v3, v79 offset:1068
	ds_write_b32 v3, v80 offset:2112
	ds_write_b32 v3, v81 offset:2116
	ds_write_b32 v3, v82 offset:2120
	ds_write_b32 v3, v83 offset:2124
	ds_write_b32 v3, v84 offset:3168
	ds_write_b32 v3, v85 offset:3172
	ds_write_b32 v3, v86 offset:3176
	ds_write_b32 v3, v87 offset:3180
	ds_write_b32 v3, v88 offset:4224
	ds_write_b32 v3, v89 offset:4228
	ds_write_b32 v3, v90 offset:4232
	ds_write_b32 v3, v91 offset:4236
	ds_write_b32 v3, v92 offset:5280
	ds_write_b32 v3, v93 offset:5284
	ds_write_b32 v3, v94 offset:5288
	ds_write_b32 v3, v95 offset:5292
	ds_write_b32 v3, v96 offset:6336
	ds_write_b32 v3, v97 offset:6340
	ds_write_b32 v3, v98 offset:6344
	ds_write_b32 v3, v99 offset:6348
	ds_write_b32 v3, v100 offset:7392
	ds_write_b32 v3, v101 offset:7396
	ds_write_b32 v3, v102 offset:7400
	ds_write_b32 v3, v103 offset:7404
	s_mov_b32 s32, s42
	s_mov_b32 s33, s43
	s_lshl_b32 s49, s44, 3
	v_mad_u32_u24 v6, v1, s44, v2
	s_waitcnt lgkmcnt(0)
	ds_read_b32 v104, v4 offset:0
	ds_read_b32 v105, v4 offset:132
	ds_read_b32 v106, v4 offset:264
	ds_read_b32 v107, v4 offset:396
	ds_read_b32 v108, v4 offset:528
	ds_read_b32 v109, v4 offset:660
	ds_read_b32 v110, v4 offset:792
	ds_read_b32 v111, v4 offset:924
	ds_read_b32 v112, v4 offset:32
	ds_read_b32 v113, v4 offset:164
	ds_read_b32 v114, v4 offset:296
	ds_read_b32 v115, v4 offset:428
	ds_read_b32 v116, v4 offset:560
	ds_read_b32 v117, v4 offset:692
	ds_read_b32 v118, v4 offset:824
	ds_read_b32 v119, v4 offset:956
	s_waitcnt lgkmcnt(8)
	v_cvt_pk_bf16_f32 v136, v104, v105
	v_cvt_pk_bf16_f32 v137, v106, v107
	v_cvt_pk_bf16_f32 v138, v108, v109
	v_cvt_pk_bf16_f32 v139, v110, v111
	global_store_dwordx4 v6, v[136:139], s[32:33] nt
	s_add_u32 s32, s32, s49
	s_addc_u32 s33, s33, 0
	ds_read_b32 v120, v4 offset:64
	ds_read_b32 v121, v4 offset:196
	ds_read_b32 v122, v4 offset:328
	ds_read_b32 v123, v4 offset:460
	ds_read_b32 v124, v4 offset:592
	ds_read_b32 v125, v4 offset:724
	ds_read_b32 v126, v4 offset:856
	ds_read_b32 v127, v4 offset:988
	s_waitcnt lgkmcnt(8)
	v_cvt_pk_bf16_f32 v140, v112, v113
	v_cvt_pk_bf16_f32 v141, v114, v115
	v_cvt_pk_bf16_f32 v142, v116, v117
	v_cvt_pk_bf16_f32 v143, v118, v119
	global_store_dwordx4 v6, v[140:143], s[32:33] nt
	s_add_u32 s32, s32, s49
	s_addc_u32 s33, s33, 0
	ds_read_b32 v128, v4 offset:96
	ds_read_b32 v129, v4 offset:228
	ds_read_b32 v130, v4 offset:360
	ds_read_b32 v131, v4 offset:492
	ds_read_b32 v132, v4 offset:624
	ds_read_b32 v133, v4 offset:756
	ds_read_b32 v134, v4 offset:888
	ds_read_b32 v135, v4 offset:1020
	s_waitcnt lgkmcnt(8)
	v_cvt_pk_bf16_f32 v136, v120, v121
	v_cvt_pk_bf16_f32 v137, v122, v123
	v_cvt_pk_bf16_f32 v138, v124, v125
	v_cvt_pk_bf16_f32 v139, v126, v127
	global_store_dwordx4 v6, v[136:139], s[32:33] nt
	s_add_u32 s32, s32, s49
	s_addc_u32 s33, s33, 0
	s_waitcnt lgkmcnt(0)
	v_cvt_pk_bf16_f32 v140, v128, v129
	v_cvt_pk_bf16_f32 v141, v130, v131
	v_cvt_pk_bf16_f32 v142, v132, v133
	v_cvt_pk_bf16_f32 v143, v134, v135
	global_store_dwordx4 v6, v[140:143], s[32:33] nt
	s_add_u32 s32, s32, s49
	s_addc_u32 s33, s33, 0
	s_cmp_ge_u32 s20, 11264
	s_cbranch_scc1 .Ltt7_0_dr5
	s_cmp_lt_u32 s20, 4096
	s_cbranch_scc1 .Ltt7_0_r6_s0
	s_sub_u32 s25, s20, 4096
	s_lshr_b32 s27, s25, 8
	s_and_b32 s31, s25, 255
	s_mul_i32 s35, s27, 0x200000
	s_lshl_b32 s41, s31, 7
	s_add_u32 s35, s35, s41
	s_add_u32 s0, s66, s35
	s_addc_u32 s1, s67, 0
	s_mul_i32 s35, s31, 0x20000
	s_lshl_b32 s41, s27, 7
	s_add_u32 s35, s35, s41
	s_add_u32 s42, s68, s35
	s_addc_u32 s43, s69, 0
	s_mov_b32 s5, 0x8000
	s_mov_b32 s6, 0x40000
	s_mov_b32 s44, 0x1000
	s_branch .Ltt7_0_r6_e

.Ltt7_0_r6_e:
	v_mad_u32_u24 v5, v1, s5, v2
	global_load_dwordx4 v[72:75], v5, s[0:1] nt
	s_add_u32 s0, s0, s6
	s_addc_u32 s1, s1, 0
	global_load_dwordx4 v[76:79], v5, s[0:1] nt
	s_add_u32 s0, s0, s6
	s_addc_u32 s1, s1, 0
	global_load_dwordx4 v[80:83], v5, s[0:1] nt
	s_add_u32 s0, s0, s6
	s_addc_u32 s1, s1, 0
	global_load_dwordx4 v[84:87], v5, s[0:1] nt
	s_add_u32 s0, s0, s6
	s_addc_u32 s1, s1, 0
	global_load_dwordx4 v[88:91], v5, s[0:1] nt
	s_add_u32 s0, s0, s6
	s_addc_u32 s1, s1, 0
	global_load_dwordx4 v[92:95], v5, s[0:1] nt
	s_add_u32 s0, s0, s6
	s_addc_u32 s1, s1, 0
	global_load_dwordx4 v[96:99], v5, s[0:1] nt
	s_add_u32 s0, s0, s6
	s_addc_u32 s1, s1, 0
	global_load_dwordx4 v[100:103], v5, s[0:1] nt
	s_add_u32 s0, s0, s6
	s_addc_u32 s1, s1, 0
	s_add_u32 s20, s20, s23
	s_waitcnt vmcnt(24)
	ds_write_b32 v3, v8 offset:0
	ds_write_b32 v3, v9 offset:4
	ds_write_b32 v3, v10 offset:8
	ds_write_b32 v3, v11 offset:12
	ds_write_b32 v3, v12 offset:1056
	ds_write_b32 v3, v13 offset:1060
	ds_write_b32 v3, v14 offset:1064
	ds_write_b32 v3, v15 offset:1068
	ds_write_b32 v3, v16 offset:2112
	ds_write_b32 v3, v17 offset:2116
	ds_write_b32 v3, v18 offset:2120
	ds_write_b32 v3, v19 offset:2124
	ds_write_b32 v3, v20 offset:3168
	ds_write_b32 v3, v21 offset:3172
	ds_write_b32 v3, v22 offset:3176
	ds_write_b32 v3, v23 offset:3180
	ds_write_b32 v3, v24 offset:4224
	ds_write_b32 v3, v25 offset:4228
	ds_write_b32 v3, v26 offset:4232
	ds_write_b32 v3, v27 offset:4236
	ds_write_b32 v3, v28 offset:5280
	ds_write_b32 v3, v29 offset:5284
	ds_write_b32 v3, v30 offset:5288
	ds_write_b32 v3, v31 offset:5292
	ds_write_b32 v3, v32 offset:6336
	ds_write_b32 v3, v33 offset:6340
	ds_write_b32 v3, v34 offset:6344
	ds_write_b32 v3, v35 offset:6348
	ds_write_b32 v3, v36 offset:7392
	ds_write_b32 v3, v37 offset:7396
	ds_write_b32 v3, v38 offset:7400
	ds_write_b32 v3, v39 offset:7404
	s_mov_b32 s32, s2
	s_mov_b32 s33, s3
	s_lshl_b32 s49, s7, 3
	v_mad_u32_u24 v6, v1, s7, v2
	s_waitcnt lgkmcnt(0)
	ds_read_b32 v104, v4 offset:0
	ds_read_b32 v105, v4 offset:132
	ds_read_b32 v106, v4 offset:264
	ds_read_b32 v107, v4 offset:396
	ds_read_b32 v108, v4 offset:528
	ds_read_b32 v109, v4 offset:660
	ds_read_b32 v110, v4 offset:792
	ds_read_b32 v111, v4 offset:924
	ds_read_b32 v112, v4 offset:32
	ds_read_b32 v113, v4 offset:164
	ds_read_b32 v114, v4 offset:296
	ds_read_b32 v115, v4 offset:428
	ds_read_b32 v116, v4 offset:560
	ds_read_b32 v117, v4 offset:692
	ds_read_b32 v118, v4 offset:824
	ds_read_b32 v119, v4 offset:956
	s_waitcnt lgkmcnt(8)
	v_cvt_pk_bf16_f32 v136, v104, v105
	v_cvt_pk_bf16_f32 v137, v106, v107
	v_cvt_pk_bf16_f32 v138, v108, v109
	v_cvt_pk_bf16_f32 v139, v110, v111
	global_store_dwordx4 v6, v[136:139], s[32:33] nt
	s_add_u32 s32, s32, s49
	s_addc_u32 s33, s33, 0
	ds_read_b32 v120, v4 offset:64
	ds_read_b32 v121, v4 offset:196
	ds_read_b32 v122, v4 offset:328
	ds_read_b32 v123, v4 offset:460
	ds_read_b32 v124, v4 offset:592
	ds_read_b32 v125, v4 offset:724
	ds_read_b32 v126, v4 offset:856
	ds_read_b32 v127, v4 offset:988
	s_waitcnt lgkmcnt(8)
	v_cvt_pk_bf16_f32 v140, v112, v113
	v_cvt_pk_bf16_f32 v141, v114, v115
	v_cvt_pk_bf16_f32 v142, v116, v117
	v_cvt_pk_bf16_f32 v143, v118, v119
	global_store_dwordx4 v6, v[140:143], s[32:33] nt
	s_add_u32 s32, s32, s49
	s_addc_u32 s33, s33, 0
	ds_read_b32 v128, v4 offset:96
	ds_read_b32 v129, v4 offset:228
	ds_read_b32 v130, v4 offset:360
	ds_read_b32 v131, v4 offset:492
	ds_read_b32 v132, v4 offset:624
	ds_read_b32 v133, v4 offset:756
	ds_read_b32 v134, v4 offset:888
	ds_read_b32 v135, v4 offset:1020
	s_waitcnt lgkmcnt(8)
	v_cvt_pk_bf16_f32 v136, v120, v121
	v_cvt_pk_bf16_f32 v137, v122, v123
	v_cvt_pk_bf16_f32 v138, v124, v125
	v_cvt_pk_bf16_f32 v139, v126, v127
	global_store_dwordx4 v6, v[136:139], s[32:33] nt
	s_add_u32 s32, s32, s49
	s_addc_u32 s33, s33, 0
	s_waitcnt lgkmcnt(0)
	v_cvt_pk_bf16_f32 v140, v128, v129
	v_cvt_pk_bf16_f32 v141, v130, v131
	v_cvt_pk_bf16_f32 v142, v132, v133
	v_cvt_pk_bf16_f32 v143, v134, v135
	global_store_dwordx4 v6, v[140:143], s[32:33] nt
	s_add_u32 s32, s32, s49
	s_addc_u32 s33, s33, 0
	s_cmp_ge_u32 s20, 11264
	s_cbranch_scc1 .Ltt7_0_dr6
	s_cmp_lt_u32 s20, 4096
	s_cbranch_scc1 .Ltt7_0_r7_s0
	s_sub_u32 s25, s20, 4096
	s_lshr_b32 s27, s25, 8
	s_and_b32 s31, s25, 255
	s_mul_i32 s35, s27, 0x200000
	s_lshl_b32 s41, s31, 7
	s_add_u32 s35, s35, s41
	s_add_u32 s0, s66, s35
	s_addc_u32 s1, s67, 0
	s_mul_i32 s35, s31, 0x20000
	s_lshl_b32 s41, s27, 7
	s_add_u32 s35, s35, s41
	s_add_u32 s2, s68, s35
	s_addc_u32 s3, s69, 0
	s_mov_b32 s5, 0x8000
	s_mov_b32 s6, 0x40000
	s_mov_b32 s7, 0x1000
	s_branch .Ltt7_0_r7_e

.Ltt7_0_done:
	s_cmp_lg_u32 s87, 0x100
	s_cbranch_scc1 .Ltt7_1_done
	s_cmp_lt_u32 s96, 0
	s_cbranch_scc1 .Ltt7_1_done
	s_cmp_ge_u32 s96, 128
	s_cbranch_scc1 .Ltt7_1_done
	s_sub_u32 s20, s96, 0
	s_lshl_b32 s20, s20, 3
	s_add_u32 s20, s20, s93
	s_movk_i32 s23, 1024
	v_mbcnt_hi_u32_b32 v0, -1, v212
	v_and_b32_e32 v0, 63, v0
	v_lshrrev_b32_e32 v1, 3, v0
	v_and_b32_e32 v2, 7, v0
	s_lshl_b32 s25, s93, 14
	v_mul_u32_u24_e32 v3, 0x84, v1
	v_mul_u32_u24_e32 v4, 0x420, v2
	v_lshlrev_b32_e32 v2, 4, v2
	v_add3_u32 v3, v3, v2, s25
	v_lshl_add_u32 v4, v1, 2, v4
	v_add_u32_e32 v4, s25, v4
	v_and_b32_e32 v7, 4, v1
	v_and_b32_e32 v5, 3, v1
	v_lshl_add_u32 v7, v7, 1, v5
	v_readlane_b32 s62, v245, 0
	v_readlane_b32 s63, v245, 1
	s_add_u32 s64, s76, 0x6989000
	s_addc_u32 s65, s77, 0
	s_nop 0
	s_add_u32 s62, s62, 0x4000000
	s_addc_u32 s63, s63, 0
	s_cmp_ge_u32 s20, 1024
	s_cbranch_scc1 .Ltt7_1_done
	s_sub_u32 s25, s20, -7168
	s_lshr_b32 s27, s25, 8
	s_and_b32 s31, s25, 255
	s_mul_i32 s35, s27, 0x200000
	s_lshl_b32 s41, s31, 7
	s_add_u32 s35, s35, s41
	s_add_u32 s0, s62, s35
	s_addc_u32 s1, s63, 0
	s_mul_i32 s35, s31, 0x20000
	s_lshl_b32 s41, s27, 7
	s_add_u32 s35, s35, s41
	s_add_u32 s2, s64, s35
	s_addc_u32 s3, s65, 0
	s_mov_b32 s5, 0x8000
	s_mov_b32 s6, 0x40000
	s_mov_b32 s7, 0x1000
.Ltt7_1_r1_e:
	v_mad_u32_u24 v5, v1, s5, v2
	global_load_dwordx4 v[8:11], v5, s[0:1] nt
	s_add_u32 s0, s0, s6
	s_addc_u32 s1, s1, 0
	global_load_dwordx4 v[12:15], v5, s[0:1] nt
	s_add_u32 s0, s0, s6
	s_addc_u32 s1, s1, 0
	global_load_dwordx4 v[16:19], v5, s[0:1] nt
	s_add_u32 s0, s0, s6
	s_addc_u32 s1, s1, 0
	global_load_dwordx4 v[20:23], v5, s[0:1] nt
	s_add_u32 s0, s0, s6
	s_addc_u32 s1, s1, 0
	global_load_dwordx4 v[24:27], v5, s[0:1] nt
	s_add_u32 s0, s0, s6
	s_addc_u32 s1, s1, 0
	global_load_dwordx4 v[28:31], v5, s[0:1] nt
	s_add_u32 s0, s0, s6
	s_addc_u32 s1, s1, 0
	global_load_dwordx4 v[32:35], v5, s[0:1] nt
	s_add_u32 s0, s0, s6
	s_addc_u32 s1, s1, 0
	global_load_dwordx4 v[36:39], v5, s[0:1] nt
	s_add_u32 s0, s0, s6
	s_addc_u32 s1, s1, 0
	s_add_u32 s20, s20, s23
	s_cmp_ge_u32 s20, 1024
	s_cbranch_scc1 .Ltt7_1_dr1
	s_sub_u32 s25, s20, -7168
	s_lshr_b32 s27, s25, 8
	s_and_b32 s31, s25, 255
	s_mul_i32 s35, s27, 0x200000
	s_lshl_b32 s41, s31, 7
	s_add_u32 s35, s35, s41
	s_add_u32 s0, s62, s35
	s_addc_u32 s1, s63, 0
	s_mul_i32 s35, s31, 0x20000
	s_lshl_b32 s41, s27, 7
	s_add_u32 s35, s35, s41
	s_add_u32 s10, s64, s35
	s_addc_u32 s11, s65, 0
	s_mov_b32 s5, 0x8000
	s_mov_b32 s6, 0x40000
	s_mov_b32 s47, 0x1000
.Ltt7_1_r2_e:
	v_mad_u32_u24 v5, v1, s5, v2
	global_load_dwordx4 v[40:43], v5, s[0:1] nt
	s_add_u32 s0, s0, s6
	s_addc_u32 s1, s1, 0
	global_load_dwordx4 v[44:47], v5, s[0:1] nt
	s_add_u32 s0, s0, s6
	s_addc_u32 s1, s1, 0
	global_load_dwordx4 v[48:51], v5, s[0:1] nt
	s_add_u32 s0, s0, s6
	s_addc_u32 s1, s1, 0
	global_load_dwordx4 v[52:55], v5, s[0:1] nt
	s_add_u32 s0, s0, s6
	s_addc_u32 s1, s1, 0
	global_load_dwordx4 v[56:59], v5, s[0:1] nt
	s_add_u32 s0, s0, s6
	s_addc_u32 s1, s1, 0
	global_load_dwordx4 v[60:63], v5, s[0:1] nt
	s_add_u32 s0, s0, s6
	s_addc_u32 s1, s1, 0
	global_load_dwordx4 v[64:67], v5, s[0:1] nt
	s_add_u32 s0, s0, s6
	s_addc_u32 s1, s1, 0
	global_load_dwordx4 v[68:71], v5, s[0:1] nt
	s_add_u32 s0, s0, s6
	s_addc_u32 s1, s1, 0
	s_add_u32 s20, s20, s23
	s_cmp_ge_u32 s20, 1024
	s_cbranch_scc1 .Ltt7_1_dr2
	s_sub_u32 s25, s20, -7168
	s_lshr_b32 s27, s25, 8
	s_and_b32 s31, s25, 255
	s_mul_i32 s35, s27, 0x200000
	s_lshl_b32 s41, s31, 7
	s_add_u32 s35, s35, s41
	s_add_u32 s0, s62, s35
	s_addc_u32 s1, s63, 0
	s_mul_i32 s35, s31, 0x20000
	s_lshl_b32 s41, s27, 7
	s_add_u32 s35, s35, s41
	s_add_u32 s42, s64, s35
	s_addc_u32 s43, s65, 0
	s_mov_b32 s5, 0x8000
	s_mov_b32 s6, 0x40000
	s_mov_b32 s44, 0x1000
.Ltt7_1_r3_e:
	v_mad_u32_u24 v5, v1, s5, v2
	global_load_dwordx4 v[72:75], v5, s[0:1] nt
	s_add_u32 s0, s0, s6
	s_addc_u32 s1, s1, 0
	global_load_dwordx4 v[76:79], v5, s[0:1] nt
	s_add_u32 s0, s0, s6
	s_addc_u32 s1, s1, 0
	global_load_dwordx4 v[80:83], v5, s[0:1] nt
	s_add_u32 s0, s0, s6
	s_addc_u32 s1, s1, 0
	global_load_dwordx4 v[84:87], v5, s[0:1] nt
	s_add_u32 s0, s0, s6
	s_addc_u32 s1, s1, 0
	global_load_dwordx4 v[88:91], v5, s[0:1] nt
	s_add_u32 s0, s0, s6
	s_addc_u32 s1, s1, 0
	global_load_dwordx4 v[92:95], v5, s[0:1] nt
	s_add_u32 s0, s0, s6
	s_addc_u32 s1, s1, 0
	global_load_dwordx4 v[96:99], v5, s[0:1] nt
	s_add_u32 s0, s0, s6
	s_addc_u32 s1, s1, 0
	global_load_dwordx4 v[100:103], v5, s[0:1] nt
	s_add_u32 s0, s0, s6
	s_addc_u32 s1, s1, 0
	s_add_u32 s20, s20, s23
	s_waitcnt vmcnt(16)
	ds_write_b32 v3, v8 offset:0
	ds_write_b32 v3, v9 offset:4
	ds_write_b32 v3, v10 offset:8
	ds_write_b32 v3, v11 offset:12
	ds_write_b32 v3, v12 offset:1056
	ds_write_b32 v3, v13 offset:1060
	ds_write_b32 v3, v14 offset:1064
	ds_write_b32 v3, v15 offset:1068
	ds_write_b32 v3, v16 offset:2112
	ds_write_b32 v3, v17 offset:2116
	ds_write_b32 v3, v18 offset:2120
	ds_write_b32 v3, v19 offset:2124
	ds_write_b32 v3, v20 offset:3168
	ds_write_b32 v3, v21 offset:3172
	ds_write_b32 v3, v22 offset:3176
	ds_write_b32 v3, v23 offset:3180
	ds_write_b32 v3, v24 offset:4224
	ds_write_b32 v3, v25 offset:4228
	ds_write_b32 v3, v26 offset:4232
	ds_write_b32 v3, v27 offset:4236
	ds_write_b32 v3, v28 offset:5280
	ds_write_b32 v3, v29 offset:5284
	ds_write_b32 v3, v30 offset:5288
	ds_write_b32 v3, v31 offset:5292
	ds_write_b32 v3, v32 offset:6336
	ds_write_b32 v3, v33 offset:6340
	ds_write_b32 v3, v34 offset:6344
	ds_write_b32 v3, v35 offset:6348
	ds_write_b32 v3, v36 offset:7392
	ds_write_b32 v3, v37 offset:7396
	ds_write_b32 v3, v38 offset:7400
	ds_write_b32 v3, v39 offset:7404
	s_mov_b32 s32, s2
	s_mov_b32 s33, s3
	s_lshl_b32 s49, s7, 3
	v_mad_u32_u24 v6, v1, s7, v2
	s_waitcnt lgkmcnt(0)
	ds_read_b32 v104, v4 offset:0
	ds_read_b32 v105, v4 offset:132
	ds_read_b32 v106, v4 offset:264
	ds_read_b32 v107, v4 offset:396
	ds_read_b32 v108, v4 offset:528
	ds_read_b32 v109, v4 offset:660
	ds_read_b32 v110, v4 offset:792
	ds_read_b32 v111, v4 offset:924
	ds_read_b32 v112, v4 offset:32
	ds_read_b32 v113, v4 offset:164
	ds_read_b32 v114, v4 offset:296
	ds_read_b32 v115, v4 offset:428
	ds_read_b32 v116, v4 offset:560
	ds_read_b32 v117, v4 offset:692
	ds_read_b32 v118, v4 offset:824
	ds_read_b32 v119, v4 offset:956
	s_waitcnt lgkmcnt(8)
	v_cvt_pk_bf16_f32 v136, v104, v105
	v_cvt_pk_bf16_f32 v137, v106, v107
	v_cvt_pk_bf16_f32 v138, v108, v109
	v_cvt_pk_bf16_f32 v139, v110, v111
	global_store_dwordx4 v6, v[136:139], s[32:33] nt
	s_add_u32 s32, s32, s49
	s_addc_u32 s33, s33, 0
	ds_read_b32 v120, v4 offset:64
	ds_read_b32 v121, v4 offset:196
	ds_read_b32 v122, v4 offset:328
	ds_read_b32 v123, v4 offset:460
	ds_read_b32 v124, v4 offset:592
	ds_read_b32 v125, v4 offset:724
	ds_read_b32 v126, v4 offset:856
	ds_read_b32 v127, v4 offset:988
	s_waitcnt lgkmcnt(8)
	v_cvt_pk_bf16_f32 v140, v112, v113
	v_cvt_pk_bf16_f32 v141, v114, v115
	v_cvt_pk_bf16_f32 v142, v116, v117
	v_cvt_pk_bf16_f32 v143, v118, v119
	global_store_dwordx4 v6, v[140:143], s[32:33] nt
	s_add_u32 s32, s32, s49
	s_addc_u32 s33, s33, 0
	ds_read_b32 v128, v4 offset:96
	ds_read_b32 v129, v4 offset:228
	ds_read_b32 v130, v4 offset:360
	ds_read_b32 v131, v4 offset:492
	ds_read_b32 v132, v4 offset:624
	ds_read_b32 v133, v4 offset:756
	ds_read_b32 v134, v4 offset:888
	ds_read_b32 v135, v4 offset:1020
	s_waitcnt lgkmcnt(8)
	v_cvt_pk_bf16_f32 v136, v120, v121
	v_cvt_pk_bf16_f32 v137, v122, v123
	v_cvt_pk_bf16_f32 v138, v124, v125
	v_cvt_pk_bf16_f32 v139, v126, v127
	global_store_dwordx4 v6, v[136:139], s[32:33] nt
	s_add_u32 s32, s32, s49
	s_addc_u32 s33, s33, 0
	s_waitcnt lgkmcnt(0)
	v_cvt_pk_bf16_f32 v140, v128, v129
	v_cvt_pk_bf16_f32 v141, v130, v131
	v_cvt_pk_bf16_f32 v142, v132, v133
	v_cvt_pk_bf16_f32 v143, v134, v135
	global_store_dwordx4 v6, v[140:143], s[32:33] nt
	s_add_u32 s32, s32, s49
	s_addc_u32 s33, s33, 0
	s_cmp_ge_u32 s20, 1024
	s_cbranch_scc1 .Ltt7_1_dr3
	s_sub_u32 s25, s20, -7168
	s_lshr_b32 s27, s25, 8
	s_and_b32 s31, s25, 255
	s_mul_i32 s35, s27, 0x200000
	s_lshl_b32 s41, s31, 7
	s_add_u32 s35, s35, s41
	s_add_u32 s0, s62, s35
	s_addc_u32 s1, s63, 0
	s_mul_i32 s35, s31, 0x20000
	s_lshl_b32 s41, s27, 7
	s_add_u32 s35, s35, s41
	s_add_u32 s2, s64, s35
	s_addc_u32 s3, s65, 0
	s_mov_b32 s5, 0x8000
	s_mov_b32 s6, 0x40000
	s_mov_b32 s7, 0x1000

.Ltt7_1_loop:
	s_cmp_ge_u32 s20, 1024
	s_cbranch_scc1 .Ltt7_1_dr4
	s_sub_u32 s25, s20, -7168
	s_lshr_b32 s27, s25, 8
	s_and_b32 s31, s25, 255
	s_mul_i32 s35, s27, 0x200000
	s_lshl_b32 s41, s31, 7
	s_add_u32 s35, s35, s41
	s_add_u32 s0, s62, s35
	s_addc_u32 s1, s63, 0
	s_mul_i32 s35, s31, 0x20000
	s_lshl_b32 s41, s27, 7
	s_add_u32 s35, s35, s41
	s_add_u32 s10, s64, s35
	s_addc_u32 s11, s65, 0
	s_mov_b32 s5, 0x8000
	s_mov_b32 s6, 0x40000
	s_mov_b32 s47, 0x1000
.Ltt7_1_r5_e:
	v_mad_u32_u24 v5, v1, s5, v2
	global_load_dwordx4 v[40:43], v5, s[0:1] nt
	s_add_u32 s0, s0, s6
	s_addc_u32 s1, s1, 0
	global_load_dwordx4 v[44:47], v5, s[0:1] nt
	s_add_u32 s0, s0, s6
	s_addc_u32 s1, s1, 0
	global_load_dwordx4 v[48:51], v5, s[0:1] nt
	s_add_u32 s0, s0, s6
	s_addc_u32 s1, s1, 0
	global_load_dwordx4 v[52:55], v5, s[0:1] nt
	s_add_u32 s0, s0, s6
	s_addc_u32 s1, s1, 0
	global_load_dwordx4 v[56:59], v5, s[0:1] nt
	s_add_u32 s0, s0, s6
	s_addc_u32 s1, s1, 0
	global_load_dwordx4 v[60:63], v5, s[0:1] nt
	s_add_u32 s0, s0, s6
	s_addc_u32 s1, s1, 0
	global_load_dwordx4 v[64:67], v5, s[0:1] nt
	s_add_u32 s0, s0, s6
	s_addc_u32 s1, s1, 0
	global_load_dwordx4 v[68:71], v5, s[0:1] nt
	s_add_u32 s0, s0, s6
	s_addc_u32 s1, s1, 0
	s_add_u32 s20, s20, s23
	s_waitcnt vmcnt(24)
	ds_write_b32 v3, v72 offset:0
	ds_write_b32 v3, v73 offset:4
	ds_write_b32 v3, v74 offset:8
	ds_write_b32 v3, v75 offset:12
	ds_write_b32 v3, v76 offset:1056
	ds_write_b32 v3, v77 offset:1060
	ds_write_b32 v3, v78 offset:1064
	ds_write_b32 v3, v79 offset:1068
	ds_write_b32 v3, v80 offset:2112
	ds_write_b32 v3, v81 offset:2116
	ds_write_b32 v3, v82 offset:2120
	ds_write_b32 v3, v83 offset:2124
	ds_write_b32 v3, v84 offset:3168
	ds_write_b32 v3, v85 offset:3172
	ds_write_b32 v3, v86 offset:3176
	ds_write_b32 v3, v87 offset:3180
	ds_write_b32 v3, v88 offset:4224
	ds_write_b32 v3, v89 offset:4228
	ds_write_b32 v3, v90 offset:4232
	ds_write_b32 v3, v91 offset:4236
	ds_write_b32 v3, v92 offset:5280
	ds_write_b32 v3, v93 offset:5284
	ds_write_b32 v3, v94 offset:5288
	ds_write_b32 v3, v95 offset:5292
	ds_write_b32 v3, v96 offset:6336
	ds_write_b32 v3, v97 offset:6340
	ds_write_b32 v3, v98 offset:6344
	ds_write_b32 v3, v99 offset:6348
	ds_write_b32 v3, v100 offset:7392
	ds_write_b32 v3, v101 offset:7396
	ds_write_b32 v3, v102 offset:7400
	ds_write_b32 v3, v103 offset:7404
	s_mov_b32 s32, s42
	s_mov_b32 s33, s43
	s_lshl_b32 s49, s44, 3
	v_mad_u32_u24 v6, v1, s44, v2
	s_waitcnt lgkmcnt(0)
	ds_read_b32 v104, v4 offset:0
	ds_read_b32 v105, v4 offset:132
	ds_read_b32 v106, v4 offset:264
	ds_read_b32 v107, v4 offset:396
	ds_read_b32 v108, v4 offset:528
	ds_read_b32 v109, v4 offset:660
	ds_read_b32 v110, v4 offset:792
	ds_read_b32 v111, v4 offset:924
	ds_read_b32 v112, v4 offset:32
	ds_read_b32 v113, v4 offset:164
	ds_read_b32 v114, v4 offset:296
	ds_read_b32 v115, v4 offset:428
	ds_read_b32 v116, v4 offset:560
	ds_read_b32 v117, v4 offset:692
	ds_read_b32 v118, v4 offset:824
	ds_read_b32 v119, v4 offset:956
	s_waitcnt lgkmcnt(8)
	v_cvt_pk_bf16_f32 v136, v104, v105
	v_cvt_pk_bf16_f32 v137, v106, v107
	v_cvt_pk_bf16_f32 v138, v108, v109
	v_cvt_pk_bf16_f32 v139, v110, v111
	global_store_dwordx4 v6, v[136:139], s[32:33] nt
	s_add_u32 s32, s32, s49
	s_addc_u32 s33, s33, 0
	ds_read_b32 v120, v4 offset:64
	ds_read_b32 v121, v4 offset:196
	ds_read_b32 v122, v4 offset:328
	ds_read_b32 v123, v4 offset:460
	ds_read_b32 v124, v4 offset:592
	ds_read_b32 v125, v4 offset:724
	ds_read_b32 v126, v4 offset:856
	ds_read_b32 v127, v4 offset:988
	s_waitcnt lgkmcnt(8)
	v_cvt_pk_bf16_f32 v140, v112, v113
	v_cvt_pk_bf16_f32 v141, v114, v115
	v_cvt_pk_bf16_f32 v142, v116, v117
	v_cvt_pk_bf16_f32 v143, v118, v119
	global_store_dwordx4 v6, v[140:143], s[32:33] nt
	s_add_u32 s32, s32, s49
	s_addc_u32 s33, s33, 0
	ds_read_b32 v128, v4 offset:96
	ds_read_b32 v129, v4 offset:228
	ds_read_b32 v130, v4 offset:360
	ds_read_b32 v131, v4 offset:492
	ds_read_b32 v132, v4 offset:624
	ds_read_b32 v133, v4 offset:756
	ds_read_b32 v134, v4 offset:888
	ds_read_b32 v135, v4 offset:1020
	s_waitcnt lgkmcnt(8)
	v_cvt_pk_bf16_f32 v136, v120, v121
	v_cvt_pk_bf16_f32 v137, v122, v123
	v_cvt_pk_bf16_f32 v138, v124, v125
	v_cvt_pk_bf16_f32 v139, v126, v127
	global_store_dwordx4 v6, v[136:139], s[32:33] nt
	s_add_u32 s32, s32, s49
	s_addc_u32 s33, s33, 0
	s_waitcnt lgkmcnt(0)
	v_cvt_pk_bf16_f32 v140, v128, v129
	v_cvt_pk_bf16_f32 v141, v130, v131
	v_cvt_pk_bf16_f32 v142, v132, v133
	v_cvt_pk_bf16_f32 v143, v134, v135
	global_store_dwordx4 v6, v[140:143], s[32:33] nt
	s_add_u32 s32, s32, s49
	s_addc_u32 s33, s33, 0
	s_cmp_ge_u32 s20, 1024
	s_cbranch_scc1 .Ltt7_1_dr5
	s_sub_u32 s25, s20, -7168
	s_lshr_b32 s27, s25, 8
	s_and_b32 s31, s25, 255
	s_mul_i32 s35, s27, 0x200000
	s_lshl_b32 s41, s31, 7
	s_add_u32 s35, s35, s41
	s_add_u32 s0, s62, s35
	s_addc_u32 s1, s63, 0
	s_mul_i32 s35, s31, 0x20000
	s_lshl_b32 s41, s27, 7
	s_add_u32 s35, s35, s41
	s_add_u32 s42, s64, s35
	s_addc_u32 s43, s65, 0
	s_mov_b32 s5, 0x8000
	s_mov_b32 s6, 0x40000
	s_mov_b32 s44, 0x1000
.Ltt7_1_r6_e:
	v_mad_u32_u24 v5, v1, s5, v2
	global_load_dwordx4 v[72:75], v5, s[0:1] nt
	s_add_u32 s0, s0, s6
	s_addc_u32 s1, s1, 0
	global_load_dwordx4 v[76:79], v5, s[0:1] nt
	s_add_u32 s0, s0, s6
	s_addc_u32 s1, s1, 0
	global_load_dwordx4 v[80:83], v5, s[0:1] nt
	s_add_u32 s0, s0, s6
	s_addc_u32 s1, s1, 0
	global_load_dwordx4 v[84:87], v5, s[0:1] nt
	s_add_u32 s0, s0, s6
	s_addc_u32 s1, s1, 0
	global_load_dwordx4 v[88:91], v5, s[0:1] nt
	s_add_u32 s0, s0, s6
	s_addc_u32 s1, s1, 0
	global_load_dwordx4 v[92:95], v5, s[0:1] nt
	s_add_u32 s0, s0, s6
	s_addc_u32 s1, s1, 0
	global_load_dwordx4 v[96:99], v5, s[0:1] nt
	s_add_u32 s0, s0, s6
	s_addc_u32 s1, s1, 0
	global_load_dwordx4 v[100:103], v5, s[0:1] nt
	s_add_u32 s0, s0, s6
	s_addc_u32 s1, s1, 0
	s_add_u32 s20, s20, s23
	s_waitcnt vmcnt(24)
	ds_write_b32 v3, v8 offset:0
	ds_write_b32 v3, v9 offset:4
	ds_write_b32 v3, v10 offset:8
	ds_write_b32 v3, v11 offset:12
	ds_write_b32 v3, v12 offset:1056
	ds_write_b32 v3, v13 offset:1060
	ds_write_b32 v3, v14 offset:1064
	ds_write_b32 v3, v15 offset:1068
	ds_write_b32 v3, v16 offset:2112
	ds_write_b32 v3, v17 offset:2116
	ds_write_b32 v3, v18 offset:2120
	ds_write_b32 v3, v19 offset:2124
	ds_write_b32 v3, v20 offset:3168
	ds_write_b32 v3, v21 offset:3172
	ds_write_b32 v3, v22 offset:3176
	ds_write_b32 v3, v23 offset:3180
	ds_write_b32 v3, v24 offset:4224
	ds_write_b32 v3, v25 offset:4228
	ds_write_b32 v3, v26 offset:4232
	ds_write_b32 v3, v27 offset:4236
	ds_write_b32 v3, v28 offset:5280
	ds_write_b32 v3, v29 offset:5284
	ds_write_b32 v3, v30 offset:5288
	ds_write_b32 v3, v31 offset:5292
	ds_write_b32 v3, v32 offset:6336
	ds_write_b32 v3, v33 offset:6340
	ds_write_b32 v3, v34 offset:6344
	ds_write_b32 v3, v35 offset:6348
	ds_write_b32 v3, v36 offset:7392
	ds_write_b32 v3, v37 offset:7396
	ds_write_b32 v3, v38 offset:7400
	ds_write_b32 v3, v39 offset:7404
	s_mov_b32 s32, s2
	s_mov_b32 s33, s3
	s_lshl_b32 s49, s7, 3
	v_mad_u32_u24 v6, v1, s7, v2
	s_waitcnt lgkmcnt(0)
	ds_read_b32 v104, v4 offset:0
	ds_read_b32 v105, v4 offset:132
	ds_read_b32 v106, v4 offset:264
	ds_read_b32 v107, v4 offset:396
	ds_read_b32 v108, v4 offset:528
	ds_read_b32 v109, v4 offset:660
	ds_read_b32 v110, v4 offset:792
	ds_read_b32 v111, v4 offset:924
	ds_read_b32 v112, v4 offset:32
	ds_read_b32 v113, v4 offset:164
	ds_read_b32 v114, v4 offset:296
	ds_read_b32 v115, v4 offset:428
	ds_read_b32 v116, v4 offset:560
	ds_read_b32 v117, v4 offset:692
	ds_read_b32 v118, v4 offset:824
	ds_read_b32 v119, v4 offset:956
	s_waitcnt lgkmcnt(8)
	v_cvt_pk_bf16_f32 v136, v104, v105
	v_cvt_pk_bf16_f32 v137, v106, v107
	v_cvt_pk_bf16_f32 v138, v108, v109
	v_cvt_pk_bf16_f32 v139, v110, v111
	global_store_dwordx4 v6, v[136:139], s[32:33] nt
	s_add_u32 s32, s32, s49
	s_addc_u32 s33, s33, 0
	ds_read_b32 v120, v4 offset:64
	ds_read_b32 v121, v4 offset:196
	ds_read_b32 v122, v4 offset:328
	ds_read_b32 v123, v4 offset:460
	ds_read_b32 v124, v4 offset:592
	ds_read_b32 v125, v4 offset:724
	ds_read_b32 v126, v4 offset:856
	ds_read_b32 v127, v4 offset:988
	s_waitcnt lgkmcnt(8)
	v_cvt_pk_bf16_f32 v140, v112, v113
	v_cvt_pk_bf16_f32 v141, v114, v115
	v_cvt_pk_bf16_f32 v142, v116, v117
	v_cvt_pk_bf16_f32 v143, v118, v119
	global_store_dwordx4 v6, v[140:143], s[32:33] nt
	s_add_u32 s32, s32, s49
	s_addc_u32 s33, s33, 0
	ds_read_b32 v128, v4 offset:96
	ds_read_b32 v129, v4 offset:228
	ds_read_b32 v130, v4 offset:360
	ds_read_b32 v131, v4 offset:492
	ds_read_b32 v132, v4 offset:624
	ds_read_b32 v133, v4 offset:756
	ds_read_b32 v134, v4 offset:888
	ds_read_b32 v135, v4 offset:1020
	s_waitcnt lgkmcnt(8)
	v_cvt_pk_bf16_f32 v136, v120, v121
	v_cvt_pk_bf16_f32 v137, v122, v123
	v_cvt_pk_bf16_f32 v138, v124, v125
	v_cvt_pk_bf16_f32 v139, v126, v127
	global_store_dwordx4 v6, v[136:139], s[32:33] nt
	s_add_u32 s32, s32, s49
	s_addc_u32 s33, s33, 0
	s_waitcnt lgkmcnt(0)
	v_cvt_pk_bf16_f32 v140, v128, v129
	v_cvt_pk_bf16_f32 v141, v130, v131
	v_cvt_pk_bf16_f32 v142, v132, v133
	v_cvt_pk_bf16_f32 v143, v134, v135
	global_store_dwordx4 v6, v[140:143], s[32:33] nt
	s_add_u32 s32, s32, s49
	s_addc_u32 s33, s33, 0
	s_cmp_ge_u32 s20, 1024
	s_cbranch_scc1 .Ltt7_1_dr6
	s_sub_u32 s25, s20, -7168
	s_lshr_b32 s27, s25, 8
	s_and_b32 s31, s25, 255
	s_mul_i32 s35, s27, 0x200000
	s_lshl_b32 s41, s31, 7
	s_add_u32 s35, s35, s41
	s_add_u32 s0, s62, s35
	s_addc_u32 s1, s63, 0
	s_mul_i32 s35, s31, 0x20000
	s_lshl_b32 s41, s27, 7
	s_add_u32 s35, s35, s41
	s_add_u32 s2, s64, s35
	s_addc_u32 s3, s65, 0
	s_mov_b32 s5, 0x8000
	s_mov_b32 s6, 0x40000
	s_mov_b32 s7, 0x1000

.LBB0_1154:
	s_waitcnt vmcnt(0)
	s_barrier
	s_cmp_lg_u32 s87, 0x100
	s_cbranch_scc1 .Ltt10_0_done
	s_cmp_lt_u32 s96, 96
	s_cbranch_scc1 .Ltt10_0_done
	s_cmp_ge_u32 s96, 256
	s_cbranch_scc1 .Ltt10_0_done
	s_sub_u32 s20, s96, 96
	s_lshl_b32 s20, s20, 3
	s_add_u32 s20, s20, s93
	s_movk_i32 s23, 1280
	v_mbcnt_hi_u32_b32 v0, -1, v212
	v_and_b32_e32 v0, 63, v0
	v_lshrrev_b32_e32 v1, 3, v0
	v_and_b32_e32 v2, 7, v0
	s_lshl_b32 s25, s93, 14
	v_mul_u32_u24_e32 v3, 0x84, v1
	v_mul_u32_u24_e32 v4, 0x420, v2
	v_lshlrev_b32_e32 v2, 4, v2
	v_add3_u32 v3, v3, v2, s25
	v_lshl_add_u32 v4, v1, 2, v4
	v_add_u32_e32 v4, s25, v4
	v_and_b32_e32 v7, 4, v1
	v_and_b32_e32 v5, 3, v1
	v_lshl_add_u32 v7, v7, 1, v5
	v_readlane_b32 s62, v244, 39
	v_readlane_b32 s63, v244, 40
	s_add_u32 s64, s76, 0x4189000
	s_addc_u32 s65, s77, 0
	v_readlane_b32 s66, v244, 21
	v_readlane_b32 s67, v244, 22
	s_add_u32 s68, s76, 0xa989000
	s_addc_u32 s69, s77, 0
	s_nop 0
	s_add_u32 s66, s66, 0x4000000
	s_addc_u32 s67, s67, 0
	s_cmp_ge_u32 s20, 10240
	s_cbranch_scc1 .Ltt10_0_done
	s_cmp_lt_u32 s20, 2048
	s_cbranch_scc1 .Ltt10_0_r1_s0
	s_sub_u32 s25, s20, 2048
	s_lshr_b32 s27, s25, 6
	s_and_b32 s31, s25, 63
	s_mul_i32 s35, s27, 0x80000
	s_lshl_b32 s41, s31, 7
	s_add_u32 s35, s35, s41
	s_add_u32 s0, s66, s35
	s_addc_u32 s1, s67, 0
	s_mul_i32 s35, s31, 0x80000
	s_lshl_b32 s41, s27, 7
	s_add_u32 s35, s35, s41
	s_add_u32 s2, s68, s35
	s_addc_u32 s3, s69, 0
	s_mov_b32 s5, 0x2000
	s_mov_b32 s6, 0x10000
	s_mov_b32 s7, 0x4000
	s_branch .Ltt10_0_r1_e
